# GEMM K-loops: first trip peeled, first-touch MFMAs take C=0 inline, the 128 v_mov accumulator zeroing per unit removed
# speedup vs baseline: 1.0215x; 1.0215x over previous
; #define PG8_STAGE(bufoff, gbase, voff) do { _Pragma("unroll") for (int _i = 0; _i < 2; ++_i) \
;         __builtin_amdgcn_global_load_lds((const unsigned*)((const char*)(gbase) + (voff)[_i]), (PG8_LAS unsigned*)(lds + (bufoff) + ldsw + _i * 8192), 16, 0, 0); } while (0)
; #define PG8_LDA(dst, b, h) do { _Pragma("unroll") for (int m = 0; m < 4; ++m) _Pragma("unroll") for (int k = 0; k < 2; ++k) dst[m][k] = *(const PG8_LAS bf16x8*)(lds + PG8_SA(b, h) + aoff + m * 2048 + k * 1024); } while (0)
; #define PG8_LDB(dst, b, h) do { _Pragma("unroll") for (int n = 0; n < 2; ++n) _Pragma("unroll") for (int k = 0; k < 2; ++k) dst[n][k] = *(const PG8_LAS bf16x8*)(lds + PG8_SB(b, h) + boff + n * 2048 + k * 1024); } while (0)
; #define PG8_MMA(ai, bj, At, Bt) do { __builtin_amdgcn_s_setprio(1); _Pragma("unroll") for (int m = 0; m < 4; ++m) _Pragma("unroll") for (int n = 0; n < 2; ++n) _Pragma("unroll") for (int k = 0; k < 2; ++k) \
;         acc[ai][bj][m][n] = __builtin_amdgcn_mfma_f32_16x16x32_bf16(Bt[n][k], At[m][k], acc[ai][bj][m][n], 0, 0, 0); __builtin_amdgcn_s_setprio(0); } while (0)
; #define PG8_BAR __builtin_amdgcn_s_barrier()
; template <class Epi, class Sched, bool ALIGN_EPI = false, bool SP2 = false>
; __device__ __forceinline__ void gemm_phase(PG8_LAS unsigned char* lds, const Gemm g, const Sched& S, const Epi& E) {
;     ...
;         const bool has_next = S.next(ui + 1, nxt);
;         const char* nA = has_next ? (const char*)g.A + (size_t)nxt.pm * tstep : cA; const char* nB = has_next ? (const char*)g.Bt + (size_t)nxt.pn * tstep : cB;
;         for (int t = 0; t < nt; t += 2) {
;             const bool last = (t == nt - 2);
;             const char* a1 = cA + (size_t)(t + 1) * kstep;
;             const char* a2 = last ? nA : cA + (size_t)(t + 2) * kstep; const char* b2 = last ? nB : cB + (size_t)(t + 2) * kstep;
;             const char* a3 = a2 + kstep; const char* b3 = b2 + kstep;
;             if (last && has_next) S.a_ready(nxt);
;             if constexpr (SP2) {
;             PG8_LDB(B0, 0, 0); PG8_LDB(B1, 0, 1); PG8_SCHED; PG8_LDA(At, 0, 0); PG8_STAGE(PG8_SA(1, 1), a1 + hstep, voffA);
;             PG8_WAIT_V(8); PG8_WAIT_L(0); PG8_BAR; PG8_MMA(0, 0, At, B0); PG8_MMA(0, 1, At, B1); PG8_BAR; PG8_SCHED;
;             PG8_LDA(At, 0, 1); PG8_STAGE(PG8_SB(0, 0), b2, voffB); PG8_STAGE(PG8_SB(0, 1), b2 + hstep, voffB); PG8_STAGE(PG8_SA(0, 0), a2, voffA);
.LBB0_151:
	s_ashr_i32 s83, s82, 31
	s_lshl_b64 s[10:11], s[82:83], 19
	s_add_u32 s84, s0, s10
	s_addc_u32 s85, s1, s11
	s_and_b64 s[10:11], s[4:5], exec
	s_cselect_b32 s10, s85, s7
	s_cselect_b32 s11, s84, s6
	s_ashr_i32 s81, s80, 31
	s_lshl_b64 s[14:15], s[80:81], 19
	s_add_u32 s86, s48, s14
	s_addc_u32 s87, s49, s15
	s_and_b64 s[14:15], s[4:5], exec
	s_cselect_b32 s13, s87, s9
	s_cselect_b32 s14, s86, s8
	s_add_u32 s6, s6, 0x44000
	s_addc_u32 s7, s7, 0
	s_add_u32 s8, s8, 0x8000
	s_addc_u32 s9, s9, 0
	s_mov_b32 s15, -2
	s_waitcnt lgkmcnt(0)
	ds_read_b128 v[130:133], v177
	ds_read_b128 v[134:137], v177 offset:1024
	ds_read_b128 v[138:141], v177 offset:2048
	ds_read_b128 v[142:145], v177 offset:3072
	ds_read_b128 v[146:149], v178
	ds_read_b128 v[150:153], v178 offset:1024
	ds_read_b128 v[166:169], v178 offset:2048
	ds_read_b128 v[170:173], v178 offset:3072
	s_add_u32 s36, s6, 0xfffc4000
	s_addc_u32 s37, s7, -1
	s_cmp_eq_u32 s15, 12
	s_cselect_b32 s37, s10, s37
	s_cselect_b32 s36, s11, s36
	s_cselect_b32 s39, s13, s9
	s_cselect_b32 s38, s14, s8
	v_lshl_add_u64 v[174:175], s[6:7], 0, v[154:155]
	s_add_i32 m0, s68, 0xc000
	ds_read_b128 v[184:187], v179
	ds_read_b128 v[188:191], v179 offset:1024
	ds_read_b128 v[192:195], v179 offset:2048
	ds_read_b128 v[196:199], v179 offset:3072
	ds_read_b128 v[202:205], v179 offset:4096
	ds_read_b128 v[206:209], v179 offset:5120
	ds_read_b128 v[210:213], v179 offset:6144
	ds_read_b128 v[214:217], v179 offset:7168
	global_load_lds_dwordx4 v[174:175], off
	v_lshl_add_u64 v[174:175], v[174:175], 0, s[34:35]
	s_add_i32 m0, s68, 0xe000
	s_nop 0
	global_load_lds_dwordx4 v[174:175], off
	s_waitcnt vmcnt(8)
	s_waitcnt lgkmcnt(0)
	s_barrier
	s_setprio 1
	s_waitcnt lgkmcnt(0)
	v_mfma_f32_16x16x32_bf16 v[126:129], v[130:133], v[184:187], 0
	v_mfma_f32_16x16x32_bf16 v[122:125], v[138:141], v[184:187], 0
	v_mfma_f32_16x16x32_bf16 v[110:113], v[130:133], v[192:195], 0
	v_mfma_f32_16x16x32_bf16 v[106:109], v[138:141], v[192:195], 0
	v_mfma_f32_16x16x32_bf16 v[94:97], v[130:133], v[202:205], 0
	v_mfma_f32_16x16x32_bf16 v[90:93], v[138:141], v[202:205], 0
	v_mfma_f32_16x16x32_bf16 v[78:81], v[130:133], v[210:213], 0
	v_mfma_f32_16x16x32_bf16 v[74:77], v[138:141], v[210:213], 0
	v_mfma_f32_16x16x32_bf16 v[126:129], v[134:137], v[188:191], v[126:129]
	v_mfma_f32_16x16x32_bf16 v[122:125], v[142:145], v[188:191], v[122:125]
	v_mfma_f32_16x16x32_bf16 v[110:113], v[134:137], v[196:199], v[110:113]
	v_mfma_f32_16x16x32_bf16 v[106:109], v[142:145], v[196:199], v[106:109]
	v_mfma_f32_16x16x32_bf16 v[94:97], v[134:137], v[206:209], v[94:97]
	v_mfma_f32_16x16x32_bf16 v[90:93], v[142:145], v[206:209], v[90:93]
	v_mfma_f32_16x16x32_bf16 v[78:81], v[134:137], v[214:217], v[78:81]
	v_mfma_f32_16x16x32_bf16 v[74:77], v[142:145], v[214:217], v[74:77]
	s_setprio 0
	s_setprio 1
	v_mfma_f32_16x16x32_bf16 v[118:121], v[146:149], v[184:187], 0
	v_mfma_f32_16x16x32_bf16 v[114:117], v[166:169], v[184:187], 0
	v_mfma_f32_16x16x32_bf16 v[102:105], v[146:149], v[192:195], 0
	v_mfma_f32_16x16x32_bf16 v[98:101], v[166:169], v[192:195], 0
	v_mfma_f32_16x16x32_bf16 v[86:89], v[146:149], v[202:205], 0
	v_mfma_f32_16x16x32_bf16 v[82:85], v[166:169], v[202:205], 0
	v_mfma_f32_16x16x32_bf16 v[70:73], v[146:149], v[210:213], 0
	v_mfma_f32_16x16x32_bf16 v[66:69], v[166:169], v[210:213], 0
	v_mfma_f32_16x16x32_bf16 v[118:121], v[150:153], v[188:191], v[118:121]
	v_mfma_f32_16x16x32_bf16 v[114:117], v[170:173], v[188:191], v[114:117]
	v_mfma_f32_16x16x32_bf16 v[102:105], v[150:153], v[196:199], v[102:105]
	v_mfma_f32_16x16x32_bf16 v[98:101], v[170:173], v[196:199], v[98:101]
	v_mfma_f32_16x16x32_bf16 v[86:89], v[150:153], v[206:209], v[86:89]
	v_mfma_f32_16x16x32_bf16 v[82:85], v[170:173], v[206:209], v[82:85]
	v_mfma_f32_16x16x32_bf16 v[70:73], v[150:153], v[214:217], v[70:73]
	v_mfma_f32_16x16x32_bf16 v[66:69], v[170:173], v[214:217], v[66:69]
	s_setprio 0
	s_barrier
	v_lshl_add_u64 v[174:175], s[38:39], 0, v[154:155]
	s_add_i32 s38, s93, s33
	s_mov_b32 m0, s38
	ds_read_b128 v[184:187], v179 offset:16384
	ds_read_b128 v[188:191], v179 offset:17408
	ds_read_b128 v[192:195], v179 offset:18432
	ds_read_b128 v[196:199], v179 offset:19456
	ds_read_b128 v[202:205], v179 offset:20480
	ds_read_b128 v[206:209], v179 offset:21504
	ds_read_b128 v[210:213], v179 offset:22528
	ds_read_b128 v[214:217], v179 offset:23552
	global_load_lds_dwordx4 v[174:175], off
	v_lshl_add_u64 v[218:219], v[174:175], 0, s[34:35]
	s_add_i32 m0, s38, 0x2000
	s_add_i32 s38, s94, s33
	global_load_lds_dwordx4 v[218:219], off
	v_lshl_add_u64 v[218:219], v[174:175], 0, s[52:53]
	s_mov_b32 m0, s38
	s_nop 0
	global_load_lds_dwordx4 v[218:219], off
	v_lshl_add_u64 v[218:219], v[174:175], 0, s[54:55]
	s_add_i32 m0, s38, 0x2000
	s_nop 0
	global_load_lds_dwordx4 v[218:219], off
	v_lshl_add_u64 v[218:219], s[36:37], 0, v[154:155]
	s_mov_b32 m0, s68
	v_lshl_add_u64 v[220:221], v[218:219], 0, s[34:35]
	global_load_lds_dwordx4 v[218:219], off
	s_mov_b32 m0, s69
	s_nop 0
	global_load_lds_dwordx4 v[220:221], off
	s_waitcnt vmcnt(8)
	s_waitcnt lgkmcnt(0)
	s_barrier
; #define PG8_STAGE(bufoff, gbase, voff) do { _Pragma("unroll") for (int _i = 0; _i < 2; ++_i) \
;         __builtin_amdgcn_global_load_lds((const unsigned*)((const char*)(gbase) + (voff)[_i]), (PG8_LAS unsigned*)(lds + (bufoff) + ldsw + _i * 8192), 16, 0, 0); } while (0)
; #define PG8_LDA(dst, b, h) do { _Pragma("unroll") for (int m = 0; m < 4; ++m) _Pragma("unroll") for (int k = 0; k < 2; ++k) dst[m][k] = *(const PG8_LAS bf16x8*)(lds + PG8_SA(b, h) + aoff + m * 2048 + k * 1024); } while (0)
; #define PG8_LDB(dst, b, h) do { _Pragma("unroll") for (int n = 0; n < 2; ++n) _Pragma("unroll") for (int k = 0; k < 2; ++k) dst[n][k] = *(const PG8_LAS bf16x8*)(lds + PG8_SB(b, h) + boff + n * 2048 + k * 1024); } while (0)
; #define PG8_MMA(ai, bj, At, Bt) do { __builtin_amdgcn_s_setprio(1); _Pragma("unroll") for (int m = 0; m < 4; ++m) _Pragma("unroll") for (int n = 0; n < 2; ++n) _Pragma("unroll") for (int k = 0; k < 2; ++k) \
;         acc[ai][bj][m][n] = __builtin_amdgcn_mfma_f32_16x16x32_bf16(Bt[n][k], At[m][k], acc[ai][bj][m][n], 0, 0, 0); __builtin_amdgcn_s_setprio(0); } while (0)
; #define PG8_WAIT_V(n) asm volatile("s_waitcnt vmcnt(" #n ")" ::: "memory")
; #define PG8_WAIT_L(n) asm volatile("s_waitcnt lgkmcnt(" #n ")" ::: "memory")
; #define PG8_BAR __builtin_amdgcn_s_barrier()
; #define PG8_SCHED __builtin_amdgcn_sched_barrier(0)
; template <class Epi, class Sched, bool ALIGN_EPI = false, bool SP2 = false>
; __device__ __forceinline__ void gemm_phase(PG8_LAS unsigned char* lds, const Gemm g, const Sched& S, const Epi& E) {
;     ...
;             PG8_WAIT_V(8); PG8_WAIT_L(0); PG8_BAR; PG8_MMA(1, 0, At, B0); PG8_MMA(1, 1, At, B1); PG8_BAR; PG8_SCHED;
;             PG8_LDB(B0, 1, 0); PG8_LDB(B1, 1, 1); PG8_SCHED; PG8_LDA(At, 1, 0); PG8_STAGE(PG8_SA(0, 1), a2 + hstep, voffA);
;             PG8_WAIT_V(8); PG8_WAIT_L(0); PG8_BAR; PG8_MMA(0, 0, At, B0); PG8_MMA(0, 1, At, B1); PG8_BAR; PG8_SCHED;
	s_setprio 1
	s_waitcnt lgkmcnt(0)
	v_mfma_f32_16x16x32_bf16 v[62:65], v[130:133], v[184:187], 0
	v_mfma_f32_16x16x32_bf16 v[58:61], v[138:141], v[184:187], 0
	v_mfma_f32_16x16x32_bf16 v[46:49], v[130:133], v[192:195], 0
	v_mfma_f32_16x16x32_bf16 v[42:45], v[138:141], v[192:195], 0
	v_mfma_f32_16x16x32_bf16 v[30:33], v[130:133], v[202:205], 0
	v_mfma_f32_16x16x32_bf16 v[26:29], v[138:141], v[202:205], 0
	v_mfma_f32_16x16x32_bf16 v[14:17], v[130:133], v[210:213], 0
	v_mfma_f32_16x16x32_bf16 v[10:13], v[138:141], v[210:213], 0
	v_mfma_f32_16x16x32_bf16 v[62:65], v[134:137], v[188:191], v[62:65]
	v_mfma_f32_16x16x32_bf16 v[58:61], v[142:145], v[188:191], v[58:61]
	v_mfma_f32_16x16x32_bf16 v[46:49], v[134:137], v[196:199], v[46:49]
	v_mfma_f32_16x16x32_bf16 v[42:45], v[142:145], v[196:199], v[42:45]
	v_mfma_f32_16x16x32_bf16 v[30:33], v[134:137], v[206:209], v[30:33]
	v_mfma_f32_16x16x32_bf16 v[26:29], v[142:145], v[206:209], v[26:29]
	v_mfma_f32_16x16x32_bf16 v[14:17], v[134:137], v[214:217], v[14:17]
	v_mfma_f32_16x16x32_bf16 v[10:13], v[142:145], v[214:217], v[10:13]
	s_setprio 0
	s_setprio 1
	v_mfma_f32_16x16x32_bf16 v[54:57], v[146:149], v[184:187], 0
	v_mfma_f32_16x16x32_bf16 v[50:53], v[166:169], v[184:187], 0
	v_mfma_f32_16x16x32_bf16 v[38:41], v[146:149], v[192:195], 0
	v_mfma_f32_16x16x32_bf16 v[34:37], v[166:169], v[192:195], 0
	v_mfma_f32_16x16x32_bf16 v[22:25], v[146:149], v[202:205], 0
	v_mfma_f32_16x16x32_bf16 v[18:21], v[166:169], v[202:205], 0
	v_mfma_f32_16x16x32_bf16 v[6:9], v[146:149], v[210:213], 0
	v_mfma_f32_16x16x32_bf16 v[2:5], v[166:169], v[210:213], 0
	v_mfma_f32_16x16x32_bf16 v[54:57], v[150:153], v[188:191], v[54:57]
	v_mfma_f32_16x16x32_bf16 v[50:53], v[170:173], v[188:191], v[50:53]
	v_mfma_f32_16x16x32_bf16 v[38:41], v[150:153], v[196:199], v[38:41]
	v_mfma_f32_16x16x32_bf16 v[34:37], v[170:173], v[196:199], v[34:37]
	v_mfma_f32_16x16x32_bf16 v[22:25], v[150:153], v[206:209], v[22:25]
	v_mfma_f32_16x16x32_bf16 v[18:21], v[170:173], v[206:209], v[18:21]
	v_mfma_f32_16x16x32_bf16 v[6:9], v[150:153], v[214:217], v[6:9]
	v_mfma_f32_16x16x32_bf16 v[2:5], v[170:173], v[214:217], v[2:5]
	s_setprio 0
	s_barrier
	s_add_i32 s36, 0, 0x18000
	s_add_i32 s37, 0, 0x1c000
	v_add_u32_e32 v142, s36, v159
	v_add_u32_e32 v156, s37, v159
	ds_read_b128 v[130:133], v142
	ds_read_b128 v[134:137], v142 offset:1024
	ds_read_b128 v[138:141], v142 offset:2048
	ds_read_b128 v[142:145], v142 offset:3072
	ds_read_b128 v[146:149], v156
	ds_read_b128 v[150:153], v156 offset:1024
	ds_read_b128 v[166:169], v156 offset:2048
	ds_read_b128 v[170:173], v156 offset:3072
	s_mov_b32 m0, s70
	v_lshl_add_u64 v[220:221], v[218:219], 0, s[52:53]
	ds_read_b128 v[184:187], v179 offset:32768
	ds_read_b128 v[188:191], v179 offset:33792
	ds_read_b128 v[192:195], v179 offset:34816
	ds_read_b128 v[196:199], v179 offset:35840
	ds_read_b128 v[202:205], v179 offset:36864
	ds_read_b128 v[206:209], v179 offset:37888
	ds_read_b128 v[210:213], v179 offset:38912
	ds_read_b128 v[214:217], v179 offset:39936
	global_load_lds_dwordx4 v[220:221], off
	v_lshl_add_u64 v[220:221], v[218:219], 0, s[54:55]
	s_mov_b32 m0, s71
	s_nop 0
	global_load_lds_dwordx4 v[220:221], off
	s_waitcnt vmcnt(8)
	s_waitcnt lgkmcnt(0)
	s_barrier
	s_setprio 1
	s_waitcnt lgkmcnt(0)
	v_mfma_f32_16x16x32_bf16 v[126:129], v[130:133], v[184:187], v[126:129]
	v_mfma_f32_16x16x32_bf16 v[122:125], v[138:141], v[184:187], v[122:125]
	v_mfma_f32_16x16x32_bf16 v[110:113], v[130:133], v[192:195], v[110:113]
	v_mfma_f32_16x16x32_bf16 v[106:109], v[138:141], v[192:195], v[106:109]
	v_mfma_f32_16x16x32_bf16 v[94:97], v[130:133], v[202:205], v[94:97]
	v_mfma_f32_16x16x32_bf16 v[90:93], v[138:141], v[202:205], v[90:93]
	v_mfma_f32_16x16x32_bf16 v[78:81], v[130:133], v[210:213], v[78:81]
	v_mfma_f32_16x16x32_bf16 v[74:77], v[138:141], v[210:213], v[74:77]
	v_mfma_f32_16x16x32_bf16 v[126:129], v[134:137], v[188:191], v[126:129]
	v_mfma_f32_16x16x32_bf16 v[122:125], v[142:145], v[188:191], v[122:125]
	v_mfma_f32_16x16x32_bf16 v[110:113], v[134:137], v[196:199], v[110:113]
	v_mfma_f32_16x16x32_bf16 v[106:109], v[142:145], v[196:199], v[106:109]
	v_mfma_f32_16x16x32_bf16 v[94:97], v[134:137], v[206:209], v[94:97]
	v_mfma_f32_16x16x32_bf16 v[90:93], v[142:145], v[206:209], v[90:93]
	v_mfma_f32_16x16x32_bf16 v[78:81], v[134:137], v[214:217], v[78:81]
	v_mfma_f32_16x16x32_bf16 v[74:77], v[142:145], v[214:217], v[74:77]
	s_setprio 0
	s_setprio 1
	v_mfma_f32_16x16x32_bf16 v[118:121], v[146:149], v[184:187], v[118:121]
	v_mfma_f32_16x16x32_bf16 v[114:117], v[166:169], v[184:187], v[114:117]
	v_mfma_f32_16x16x32_bf16 v[102:105], v[146:149], v[192:195], v[102:105]
	v_mfma_f32_16x16x32_bf16 v[98:101], v[166:169], v[192:195], v[98:101]
	v_mfma_f32_16x16x32_bf16 v[86:89], v[146:149], v[202:205], v[86:89]
	v_mfma_f32_16x16x32_bf16 v[82:85], v[166:169], v[202:205], v[82:85]
	v_mfma_f32_16x16x32_bf16 v[70:73], v[146:149], v[210:213], v[70:73]
	v_mfma_f32_16x16x32_bf16 v[66:69], v[166:169], v[210:213], v[66:69]
	v_mfma_f32_16x16x32_bf16 v[118:121], v[150:153], v[188:191], v[118:121]
	v_mfma_f32_16x16x32_bf16 v[114:117], v[170:173], v[188:191], v[114:117]
	v_mfma_f32_16x16x32_bf16 v[102:105], v[150:153], v[196:199], v[102:105]
	v_mfma_f32_16x16x32_bf16 v[98:101], v[170:173], v[196:199], v[98:101]
	v_mfma_f32_16x16x32_bf16 v[86:89], v[150:153], v[206:209], v[86:89]
	v_mfma_f32_16x16x32_bf16 v[82:85], v[170:173], v[206:209], v[82:85]
	v_mfma_f32_16x16x32_bf16 v[70:73], v[150:153], v[214:217], v[70:73]
	v_mfma_f32_16x16x32_bf16 v[66:69], v[170:173], v[214:217], v[66:69]
	s_setprio 0
	s_barrier
; #define PG8_STAGE(bufoff, gbase, voff) do { _Pragma("unroll") for (int _i = 0; _i < 2; ++_i) \
;         __builtin_amdgcn_global_load_lds((const unsigned*)((const char*)(gbase) + (voff)[_i]), (PG8_LAS unsigned*)(lds + (bufoff) + ldsw + _i * 8192), 16, 0, 0); } while (0)
; #define PG8_LDA(dst, b, h) do { _Pragma("unroll") for (int m = 0; m < 4; ++m) _Pragma("unroll") for (int k = 0; k < 2; ++k) dst[m][k] = *(const PG8_LAS bf16x8*)(lds + PG8_SA(b, h) + aoff + m * 2048 + k * 1024); } while (0)
; #define PG8_MMA(ai, bj, At, Bt) do { __builtin_amdgcn_s_setprio(1); _Pragma("unroll") for (int m = 0; m < 4; ++m) _Pragma("unroll") for (int n = 0; n < 2; ++n) _Pragma("unroll") for (int k = 0; k < 2; ++k) \
;         acc[ai][bj][m][n] = __builtin_amdgcn_mfma_f32_16x16x32_bf16(Bt[n][k], At[m][k], acc[ai][bj][m][n], 0, 0, 0); __builtin_amdgcn_s_setprio(0); } while (0)
; #define PG8_WAIT_V(n) asm volatile("s_waitcnt vmcnt(" #n ")" ::: "memory")
; #define PG8_WAIT_L(n) asm volatile("s_waitcnt lgkmcnt(" #n ")" ::: "memory")
; #define PG8_BAR __builtin_amdgcn_s_barrier()
; #define PG8_SCHED __builtin_amdgcn_sched_barrier(0)
; template <class Epi, class Sched, bool ALIGN_EPI = false, bool SP2 = false>
; __device__ __forceinline__ void gemm_phase(PG8_LAS unsigned char* lds, const Gemm g, const Sched& S, const Epi& E) {
;     ...
;         for (int t = 0; t < nt; t += 2) {
;             const bool last = (t == nt - 2);
;     ...
;             PG8_LDA(At, 1, 1); PG8_STAGE(PG8_SB(1, 0), b3, voffB); PG8_STAGE(PG8_SB(1, 1), b3 + hstep, voffB); PG8_STAGE(PG8_SA(1, 0), a3, voffA);
;             PG8_WAIT_V(8); PG8_WAIT_L(0); PG8_BAR; PG8_MMA(1, 0, At, B0); PG8_MMA(1, 1, At, B1); PG8_BAR; PG8_SCHED;
	s_add_i32 s36, s36, s33
	v_lshl_add_u64 v[220:221], v[174:175], 0, s[58:59]
	s_mov_b32 m0, s36
	ds_read_b128 v[184:187], v179 offset:49152
	ds_read_b128 v[188:191], v179 offset:50176
	ds_read_b128 v[192:195], v179 offset:51200
	ds_read_b128 v[196:199], v179 offset:52224
	ds_read_b128 v[202:205], v179 offset:53248
	ds_read_b128 v[206:209], v179 offset:54272
	ds_read_b128 v[210:213], v179 offset:55296
	ds_read_b128 v[214:217], v179 offset:56320
	global_load_lds_dwordx4 v[220:221], off
	v_lshl_add_u64 v[220:221], v[174:175], 0, s[60:61]
	s_add_i32 m0, s36, 0x2000
	s_add_i32 s36, s37, s33
	global_load_lds_dwordx4 v[220:221], off
	v_lshl_add_u64 v[220:221], v[174:175], 0, s[62:63]
	s_mov_b32 m0, s36
	v_lshl_add_u64 v[174:175], v[174:175], 0, s[64:65]
	global_load_lds_dwordx4 v[220:221], off
	s_add_i32 m0, s36, 0x2000
	s_nop 0
	global_load_lds_dwordx4 v[174:175], off
	v_lshl_add_u64 v[174:175], v[218:219], 0, s[58:59]
	s_mov_b32 m0, s73
	s_nop 0
	global_load_lds_dwordx4 v[174:175], off
	v_lshl_add_u64 v[174:175], v[218:219], 0, s[60:61]
	s_mov_b32 m0, s74
	s_nop 0
	global_load_lds_dwordx4 v[174:175], off
	s_waitcnt vmcnt(8)
	s_waitcnt lgkmcnt(0)
	s_barrier
	s_setprio 1
	s_waitcnt lgkmcnt(0)
	v_mfma_f32_16x16x32_bf16 v[62:65], v[130:133], v[184:187], v[62:65]
	v_mfma_f32_16x16x32_bf16 v[58:61], v[138:141], v[184:187], v[58:61]
	v_mfma_f32_16x16x32_bf16 v[46:49], v[130:133], v[192:195], v[46:49]
	v_mfma_f32_16x16x32_bf16 v[42:45], v[138:141], v[192:195], v[42:45]
	v_mfma_f32_16x16x32_bf16 v[30:33], v[130:133], v[202:205], v[30:33]
	v_mfma_f32_16x16x32_bf16 v[26:29], v[138:141], v[202:205], v[26:29]
	v_mfma_f32_16x16x32_bf16 v[14:17], v[130:133], v[210:213], v[14:17]
	v_mfma_f32_16x16x32_bf16 v[10:13], v[138:141], v[210:213], v[10:13]
	v_mfma_f32_16x16x32_bf16 v[62:65], v[134:137], v[188:191], v[62:65]
	v_mfma_f32_16x16x32_bf16 v[58:61], v[142:145], v[188:191], v[58:61]
	v_mfma_f32_16x16x32_bf16 v[46:49], v[134:137], v[196:199], v[46:49]
	v_mfma_f32_16x16x32_bf16 v[42:45], v[142:145], v[196:199], v[42:45]
	v_mfma_f32_16x16x32_bf16 v[30:33], v[134:137], v[206:209], v[30:33]
	v_mfma_f32_16x16x32_bf16 v[26:29], v[142:145], v[206:209], v[26:29]
	v_mfma_f32_16x16x32_bf16 v[14:17], v[134:137], v[214:217], v[14:17]
	v_mfma_f32_16x16x32_bf16 v[10:13], v[142:145], v[214:217], v[10:13]
	s_setprio 0
	s_setprio 1
	v_mfma_f32_16x16x32_bf16 v[54:57], v[146:149], v[184:187], v[54:57]
	v_mfma_f32_16x16x32_bf16 v[50:53], v[166:169], v[184:187], v[50:53]
	v_mfma_f32_16x16x32_bf16 v[38:41], v[146:149], v[192:195], v[38:41]
	v_mfma_f32_16x16x32_bf16 v[34:37], v[166:169], v[192:195], v[34:37]
	v_mfma_f32_16x16x32_bf16 v[22:25], v[146:149], v[202:205], v[22:25]
	v_mfma_f32_16x16x32_bf16 v[18:21], v[166:169], v[202:205], v[18:21]
	v_mfma_f32_16x16x32_bf16 v[6:9], v[146:149], v[210:213], v[6:9]
	v_mfma_f32_16x16x32_bf16 v[2:5], v[166:169], v[210:213], v[2:5]
	v_mfma_f32_16x16x32_bf16 v[54:57], v[150:153], v[188:191], v[54:57]
	v_mfma_f32_16x16x32_bf16 v[50:53], v[170:173], v[188:191], v[50:53]
	v_mfma_f32_16x16x32_bf16 v[38:41], v[150:153], v[196:199], v[38:41]
	v_mfma_f32_16x16x32_bf16 v[34:37], v[170:173], v[196:199], v[34:37]
	v_mfma_f32_16x16x32_bf16 v[22:25], v[150:153], v[206:209], v[22:25]
	v_mfma_f32_16x16x32_bf16 v[18:21], v[170:173], v[206:209], v[18:21]
	v_mfma_f32_16x16x32_bf16 v[6:9], v[150:153], v[214:217], v[6:9]
	v_mfma_f32_16x16x32_bf16 v[2:5], v[170:173], v[214:217], v[2:5]
	s_setprio 0
	s_barrier
	s_add_i32 s15, s15, 2
	s_add_u32 s6, s6, 0x8000
	s_addc_u32 s7, s7, 0
	s_add_u32 s8, s8, 0x8000
	s_addc_u32 s9, s9, 0
	s_cmp_gt_u32 s15, 13
	s_cbranch_scc0 .LBB0_152

; #define PG8_STAGE(bufoff, gbase, voff) do { _Pragma("unroll") for (int _i = 0; _i < 2; ++_i) \
;         __builtin_amdgcn_global_load_lds((const unsigned*)((const char*)(gbase) + (voff)[_i]), (PG8_LAS unsigned*)(lds + (bufoff) + ldsw + _i * 8192), 16, 0, 0); } while (0)
; #define PG8_LDA(dst, b, h) do { _Pragma("unroll") for (int m = 0; m < 4; ++m) _Pragma("unroll") for (int k = 0; k < 2; ++k) dst[m][k] = *(const PG8_LAS bf16x8*)(lds + PG8_SA(b, h) + aoff + m * 2048 + k * 1024); } while (0)
; #define PG8_LDB(dst, b, h) do { _Pragma("unroll") for (int n = 0; n < 2; ++n) _Pragma("unroll") for (int k = 0; k < 2; ++k) dst[n][k] = *(const PG8_LAS bf16x8*)(lds + PG8_SB(b, h) + boff + n * 2048 + k * 1024); } while (0)
; #define PG8_MMA(ai, bj, At, Bt) do { __builtin_amdgcn_s_setprio(1); _Pragma("unroll") for (int m = 0; m < 4; ++m) _Pragma("unroll") for (int n = 0; n < 2; ++n) _Pragma("unroll") for (int k = 0; k < 2; ++k) \
;         acc[ai][bj][m][n] = __builtin_amdgcn_mfma_f32_16x16x32_bf16(Bt[n][k], At[m][k], acc[ai][bj][m][n], 0, 0, 0); __builtin_amdgcn_s_setprio(0); } while (0)
; #define PG8_BAR __builtin_amdgcn_s_barrier()
; template <class Epi, class Sched, bool ALIGN_EPI = false, bool SP2 = false>
; __device__ __forceinline__ void gemm_phase(PG8_LAS unsigned char* lds, const Gemm g, const Sched& S, const Epi& E) {
;     ...
;         const bool has_next = S.next(ui + 1, nxt);
;         const char* nA = has_next ? (const char*)g.A + (size_t)nxt.pm * tstep : cA; const char* nB = has_next ? (const char*)g.Bt + (size_t)nxt.pn * tstep : cB;
;         for (int t = 0; t < nt; t += 2) {
;             const bool last = (t == nt - 2);
;             const char* a1 = cA + (size_t)(t + 1) * kstep;
;             const char* a2 = last ? nA : cA + (size_t)(t + 2) * kstep; const char* b2 = last ? nB : cB + (size_t)(t + 2) * kstep;
;             const char* a3 = a2 + kstep; const char* b3 = b2 + kstep;
;             if (last && has_next) S.a_ready(nxt);
;             if constexpr (SP2) {
;             PG8_LDB(B0, 0, 0); PG8_LDB(B1, 0, 1); PG8_SCHED; PG8_LDA(At, 0, 0); PG8_STAGE(PG8_SA(1, 1), a1 + hstep, voffA);
;             PG8_WAIT_V(8); PG8_WAIT_L(0); PG8_BAR; PG8_MMA(0, 0, At, B0); PG8_MMA(0, 1, At, B1); PG8_BAR; PG8_SCHED;
;             PG8_LDA(At, 0, 1); PG8_STAGE(PG8_SB(0, 0), b2, voffB); PG8_STAGE(PG8_SB(0, 1), b2 + hstep, voffB); PG8_STAGE(PG8_SA(0, 0), a2, voffA);
.LBB0_880:
	s_ashr_i32 s55, s54, 31
	s_lshl_b64 s[48:49], s[54:55], 19
	s_add_u32 s56, s8, s48
	s_addc_u32 s57, s9, s49
	s_and_b64 s[48:49], s[6:7], exec
	s_cselect_b32 s13, s57, s63
	s_cselect_b32 s48, s56, s62
	s_ashr_i32 s53, s52, 31
	s_lshl_b64 s[50:51], s[52:53], 19
	s_add_u32 s58, s10, s50
	s_addc_u32 s59, s11, s51
	s_and_b64 s[50:51], s[6:7], exec
	s_cselect_b32 s49, s59, s65
	s_cselect_b32 s50, s58, s64
	s_add_u32 s62, s62, 0x44000
	s_addc_u32 s63, s63, 0
	s_add_u32 s51, s64, 0x8000
	s_addc_u32 s53, s65, 0
	s_mov_b32 s55, -2
	s_waitcnt lgkmcnt(0)
	ds_read_b128 v[130:133], v161
	ds_read_b128 v[134:137], v161 offset:1024
	ds_read_b128 v[144:147], v161 offset:2048
	ds_read_b128 v[148:151], v161 offset:3072
	ds_read_b128 v[152:155], v162
	ds_read_b128 v[166:169], v162 offset:1024
	ds_read_b128 v[170:173], v162 offset:2048
	ds_read_b128 v[174:177], v162 offset:3072
	s_add_u32 s61, s62, 0xfffc4000
	s_addc_u32 s64, s63, -1
	s_cmp_eq_u32 s55, 12
	s_cselect_b32 s65, s13, s64
	s_cselect_b32 s64, s48, s61
	s_cselect_b32 s81, s49, s53
	s_cselect_b32 s80, s50, s51
	v_lshl_add_u64 v[158:159], s[62:63], 0, v[138:139]
	s_add_i32 m0, s1, 0xc000
	ds_read_b128 v[178:181], v163
	ds_read_b128 v[182:185], v163 offset:1024
	ds_read_b128 v[186:189], v163 offset:2048
	ds_read_b128 v[190:193], v163 offset:3072
	ds_read_b128 v[194:197], v163 offset:4096
	ds_read_b128 v[202:205], v163 offset:5120
	ds_read_b128 v[206:209], v163 offset:6144
	ds_read_b128 v[210:213], v163 offset:7168
	global_load_lds_dwordx4 v[158:159], off
	v_lshl_add_u64 v[158:159], v[158:159], 0, s[14:15]
	s_add_i32 m0, s1, 0xe000
	s_nop 0
	global_load_lds_dwordx4 v[158:159], off
	s_waitcnt vmcnt(8)
	s_waitcnt lgkmcnt(0)
	s_barrier
	s_setprio 1
	s_waitcnt lgkmcnt(0)
	v_mfma_f32_16x16x32_bf16 v[126:129], v[130:133], v[178:181], 0
	v_mfma_f32_16x16x32_bf16 v[122:125], v[144:147], v[178:181], 0
	v_mfma_f32_16x16x32_bf16 v[110:113], v[130:133], v[186:189], 0
	v_mfma_f32_16x16x32_bf16 v[106:109], v[144:147], v[186:189], 0
	v_mfma_f32_16x16x32_bf16 v[94:97], v[130:133], v[194:197], 0
	v_mfma_f32_16x16x32_bf16 v[90:93], v[144:147], v[194:197], 0
	v_mfma_f32_16x16x32_bf16 v[78:81], v[130:133], v[206:209], 0
	v_mfma_f32_16x16x32_bf16 v[74:77], v[144:147], v[206:209], 0
	v_mfma_f32_16x16x32_bf16 v[126:129], v[134:137], v[182:185], v[126:129]
	v_mfma_f32_16x16x32_bf16 v[122:125], v[148:151], v[182:185], v[122:125]
	v_mfma_f32_16x16x32_bf16 v[110:113], v[134:137], v[190:193], v[110:113]
	v_mfma_f32_16x16x32_bf16 v[106:109], v[148:151], v[190:193], v[106:109]
	v_mfma_f32_16x16x32_bf16 v[94:97], v[134:137], v[202:205], v[94:97]
	v_mfma_f32_16x16x32_bf16 v[90:93], v[148:151], v[202:205], v[90:93]
	v_mfma_f32_16x16x32_bf16 v[78:81], v[134:137], v[210:213], v[78:81]
	v_mfma_f32_16x16x32_bf16 v[74:77], v[148:151], v[210:213], v[74:77]
	s_setprio 0
	s_setprio 1
	v_mfma_f32_16x16x32_bf16 v[118:121], v[152:155], v[178:181], 0
	v_mfma_f32_16x16x32_bf16 v[114:117], v[170:173], v[178:181], 0
	v_mfma_f32_16x16x32_bf16 v[102:105], v[152:155], v[186:189], 0
	v_mfma_f32_16x16x32_bf16 v[98:101], v[170:173], v[186:189], 0
	v_mfma_f32_16x16x32_bf16 v[86:89], v[152:155], v[194:197], 0
	v_mfma_f32_16x16x32_bf16 v[82:85], v[170:173], v[194:197], 0
	v_mfma_f32_16x16x32_bf16 v[70:73], v[152:155], v[206:209], 0
	v_mfma_f32_16x16x32_bf16 v[66:69], v[170:173], v[206:209], 0
	v_mfma_f32_16x16x32_bf16 v[118:121], v[166:169], v[182:185], v[118:121]
	v_mfma_f32_16x16x32_bf16 v[114:117], v[174:177], v[182:185], v[114:117]
	v_mfma_f32_16x16x32_bf16 v[102:105], v[166:169], v[190:193], v[102:105]
	v_mfma_f32_16x16x32_bf16 v[98:101], v[174:177], v[190:193], v[98:101]
	v_mfma_f32_16x16x32_bf16 v[86:89], v[166:169], v[202:205], v[86:89]
	v_mfma_f32_16x16x32_bf16 v[82:85], v[174:177], v[202:205], v[82:85]
	v_mfma_f32_16x16x32_bf16 v[70:73], v[166:169], v[210:213], v[70:73]
	v_mfma_f32_16x16x32_bf16 v[66:69], v[174:177], v[210:213], v[66:69]
	s_setprio 0
	s_barrier
	s_add_i32 s61, s77, s0
	v_lshl_add_u64 v[158:159], s[80:81], 0, v[138:139]
	s_mov_b32 m0, s61
	ds_read_b128 v[178:181], v163 offset:16384
	ds_read_b128 v[182:185], v163 offset:17408
	ds_read_b128 v[186:189], v163 offset:18432
	ds_read_b128 v[190:193], v163 offset:19456
	ds_read_b128 v[194:197], v163 offset:20480
	ds_read_b128 v[202:205], v163 offset:21504
	ds_read_b128 v[206:209], v163 offset:22528
	ds_read_b128 v[210:213], v163 offset:23552
	global_load_lds_dwordx4 v[158:159], off
	v_lshl_add_u64 v[198:199], v[158:159], 0, s[14:15]
	s_add_i32 m0, s61, 0x2000
	s_add_i32 s61, s78, s0
	global_load_lds_dwordx4 v[198:199], off
	v_lshl_add_u64 v[198:199], v[158:159], 0, s[16:17]
	s_mov_b32 m0, s61
	s_nop 0
	global_load_lds_dwordx4 v[198:199], off
	v_lshl_add_u64 v[198:199], v[158:159], 0, s[20:21]
	s_add_i32 m0, s61, 0x2000
	s_nop 0
	global_load_lds_dwordx4 v[198:199], off
	v_lshl_add_u64 v[198:199], s[64:65], 0, v[138:139]
	s_mov_b32 m0, s1
	v_lshl_add_u64 v[214:215], v[198:199], 0, s[14:15]
	global_load_lds_dwordx4 v[198:199], off
	s_mov_b32 m0, s33
	s_nop 0
	global_load_lds_dwordx4 v[214:215], off
	s_waitcnt vmcnt(8)
	s_waitcnt lgkmcnt(0)
	s_barrier
; #define PG8_STAGE(bufoff, gbase, voff) do { _Pragma("unroll") for (int _i = 0; _i < 2; ++_i) \
;         __builtin_amdgcn_global_load_lds((const unsigned*)((const char*)(gbase) + (voff)[_i]), (PG8_LAS unsigned*)(lds + (bufoff) + ldsw + _i * 8192), 16, 0, 0); } while (0)
; #define PG8_LDA(dst, b, h) do { _Pragma("unroll") for (int m = 0; m < 4; ++m) _Pragma("unroll") for (int k = 0; k < 2; ++k) dst[m][k] = *(const PG8_LAS bf16x8*)(lds + PG8_SA(b, h) + aoff + m * 2048 + k * 1024); } while (0)
; #define PG8_LDB(dst, b, h) do { _Pragma("unroll") for (int n = 0; n < 2; ++n) _Pragma("unroll") for (int k = 0; k < 2; ++k) dst[n][k] = *(const PG8_LAS bf16x8*)(lds + PG8_SB(b, h) + boff + n * 2048 + k * 1024); } while (0)
; #define PG8_MMA(ai, bj, At, Bt) do { __builtin_amdgcn_s_setprio(1); _Pragma("unroll") for (int m = 0; m < 4; ++m) _Pragma("unroll") for (int n = 0; n < 2; ++n) _Pragma("unroll") for (int k = 0; k < 2; ++k) \
;         acc[ai][bj][m][n] = __builtin_amdgcn_mfma_f32_16x16x32_bf16(Bt[n][k], At[m][k], acc[ai][bj][m][n], 0, 0, 0); __builtin_amdgcn_s_setprio(0); } while (0)
; #define PG8_WAIT_V(n) asm volatile("s_waitcnt vmcnt(" #n ")" ::: "memory")
; #define PG8_WAIT_L(n) asm volatile("s_waitcnt lgkmcnt(" #n ")" ::: "memory")
; #define PG8_BAR __builtin_amdgcn_s_barrier()
; #define PG8_SCHED __builtin_amdgcn_sched_barrier(0)
; template <class Epi, class Sched, bool ALIGN_EPI = false, bool SP2 = false>
; __device__ __forceinline__ void gemm_phase(PG8_LAS unsigned char* lds, const Gemm g, const Sched& S, const Epi& E) {
;     ...
;             PG8_WAIT_V(8); PG8_WAIT_L(0); PG8_BAR; PG8_MMA(1, 0, At, B0); PG8_MMA(1, 1, At, B1); PG8_BAR; PG8_SCHED;
;             PG8_LDB(B0, 1, 0); PG8_LDB(B1, 1, 1); PG8_SCHED; PG8_LDA(At, 1, 0); PG8_STAGE(PG8_SA(0, 1), a2 + hstep, voffA);
;             PG8_WAIT_V(8); PG8_WAIT_L(0); PG8_BAR; PG8_MMA(0, 0, At, B0); PG8_MMA(0, 1, At, B1); PG8_BAR; PG8_SCHED;
	s_setprio 1
	s_waitcnt lgkmcnt(0)
	v_mfma_f32_16x16x32_bf16 v[62:65], v[130:133], v[178:181], 0
	v_mfma_f32_16x16x32_bf16 v[58:61], v[144:147], v[178:181], 0
	v_mfma_f32_16x16x32_bf16 v[46:49], v[130:133], v[186:189], 0
	v_mfma_f32_16x16x32_bf16 v[42:45], v[144:147], v[186:189], 0
	v_mfma_f32_16x16x32_bf16 v[30:33], v[130:133], v[194:197], 0
	v_mfma_f32_16x16x32_bf16 v[26:29], v[144:147], v[194:197], 0
	v_mfma_f32_16x16x32_bf16 v[14:17], v[130:133], v[206:209], 0
	v_mfma_f32_16x16x32_bf16 v[10:13], v[144:147], v[206:209], 0
	v_mfma_f32_16x16x32_bf16 v[62:65], v[134:137], v[182:185], v[62:65]
	v_mfma_f32_16x16x32_bf16 v[58:61], v[148:151], v[182:185], v[58:61]
	v_mfma_f32_16x16x32_bf16 v[46:49], v[134:137], v[190:193], v[46:49]
	v_mfma_f32_16x16x32_bf16 v[42:45], v[148:151], v[190:193], v[42:45]
	v_mfma_f32_16x16x32_bf16 v[30:33], v[134:137], v[202:205], v[30:33]
	v_mfma_f32_16x16x32_bf16 v[26:29], v[148:151], v[202:205], v[26:29]
	v_mfma_f32_16x16x32_bf16 v[14:17], v[134:137], v[210:213], v[14:17]
	v_mfma_f32_16x16x32_bf16 v[10:13], v[148:151], v[210:213], v[10:13]
	s_setprio 0
	s_setprio 1
	v_mfma_f32_16x16x32_bf16 v[54:57], v[152:155], v[178:181], 0
	v_mfma_f32_16x16x32_bf16 v[50:53], v[170:173], v[178:181], 0
	v_mfma_f32_16x16x32_bf16 v[38:41], v[152:155], v[186:189], 0
	v_mfma_f32_16x16x32_bf16 v[34:37], v[170:173], v[186:189], 0
	v_mfma_f32_16x16x32_bf16 v[22:25], v[152:155], v[194:197], 0
	v_mfma_f32_16x16x32_bf16 v[18:21], v[170:173], v[194:197], 0
	v_mfma_f32_16x16x32_bf16 v[6:9], v[152:155], v[206:209], 0
	v_mfma_f32_16x16x32_bf16 v[2:5], v[170:173], v[206:209], 0
	v_mfma_f32_16x16x32_bf16 v[54:57], v[166:169], v[182:185], v[54:57]
	v_mfma_f32_16x16x32_bf16 v[50:53], v[174:177], v[182:185], v[50:53]
	v_mfma_f32_16x16x32_bf16 v[38:41], v[166:169], v[190:193], v[38:41]
	v_mfma_f32_16x16x32_bf16 v[34:37], v[174:177], v[190:193], v[34:37]
	v_mfma_f32_16x16x32_bf16 v[22:25], v[166:169], v[202:205], v[22:25]
	v_mfma_f32_16x16x32_bf16 v[18:21], v[174:177], v[202:205], v[18:21]
	v_mfma_f32_16x16x32_bf16 v[6:9], v[166:169], v[210:213], v[6:9]
	v_mfma_f32_16x16x32_bf16 v[2:5], v[174:177], v[210:213], v[2:5]
	s_setprio 0
	s_barrier
	s_add_i32 s61, 0, 0x18000
	s_add_i32 s64, 0, 0x1c000
	v_add_u32_e32 v148, s61, v160
	v_add_u32_e32 v156, s64, v160
	ds_read_b128 v[130:133], v148
	ds_read_b128 v[134:137], v148 offset:1024
	ds_read_b128 v[144:147], v148 offset:2048
	ds_read_b128 v[148:151], v148 offset:3072
	ds_read_b128 v[152:155], v156
	ds_read_b128 v[166:169], v156 offset:1024
	ds_read_b128 v[170:173], v156 offset:2048
	ds_read_b128 v[174:177], v156 offset:3072
	s_mov_b32 m0, s66
	v_lshl_add_u64 v[214:215], v[198:199], 0, s[16:17]
	ds_read_b128 v[178:181], v163 offset:32768
	ds_read_b128 v[182:185], v163 offset:33792
	ds_read_b128 v[186:189], v163 offset:34816
	ds_read_b128 v[190:193], v163 offset:35840
	ds_read_b128 v[194:197], v163 offset:36864
	ds_read_b128 v[202:205], v163 offset:37888
	ds_read_b128 v[206:209], v163 offset:38912
	ds_read_b128 v[210:213], v163 offset:39936
	global_load_lds_dwordx4 v[214:215], off
	v_lshl_add_u64 v[214:215], v[198:199], 0, s[20:21]
	s_mov_b32 m0, s67
	s_nop 0
	global_load_lds_dwordx4 v[214:215], off
	s_waitcnt vmcnt(8)
	s_waitcnt lgkmcnt(0)
	s_barrier
	s_setprio 1
	s_waitcnt lgkmcnt(0)
	v_mfma_f32_16x16x32_bf16 v[126:129], v[130:133], v[178:181], v[126:129]
	v_mfma_f32_16x16x32_bf16 v[122:125], v[144:147], v[178:181], v[122:125]
	v_mfma_f32_16x16x32_bf16 v[110:113], v[130:133], v[186:189], v[110:113]
	v_mfma_f32_16x16x32_bf16 v[106:109], v[144:147], v[186:189], v[106:109]
	v_mfma_f32_16x16x32_bf16 v[94:97], v[130:133], v[194:197], v[94:97]
	v_mfma_f32_16x16x32_bf16 v[90:93], v[144:147], v[194:197], v[90:93]
	v_mfma_f32_16x16x32_bf16 v[78:81], v[130:133], v[206:209], v[78:81]
	v_mfma_f32_16x16x32_bf16 v[74:77], v[144:147], v[206:209], v[74:77]
	v_mfma_f32_16x16x32_bf16 v[126:129], v[134:137], v[182:185], v[126:129]
	v_mfma_f32_16x16x32_bf16 v[122:125], v[148:151], v[182:185], v[122:125]
	v_mfma_f32_16x16x32_bf16 v[110:113], v[134:137], v[190:193], v[110:113]
	v_mfma_f32_16x16x32_bf16 v[106:109], v[148:151], v[190:193], v[106:109]
	v_mfma_f32_16x16x32_bf16 v[94:97], v[134:137], v[202:205], v[94:97]
	v_mfma_f32_16x16x32_bf16 v[90:93], v[148:151], v[202:205], v[90:93]
	v_mfma_f32_16x16x32_bf16 v[78:81], v[134:137], v[210:213], v[78:81]
	v_mfma_f32_16x16x32_bf16 v[74:77], v[148:151], v[210:213], v[74:77]
	s_setprio 0
	s_setprio 1
	v_mfma_f32_16x16x32_bf16 v[118:121], v[152:155], v[178:181], v[118:121]
	v_mfma_f32_16x16x32_bf16 v[114:117], v[170:173], v[178:181], v[114:117]
	v_mfma_f32_16x16x32_bf16 v[102:105], v[152:155], v[186:189], v[102:105]
	v_mfma_f32_16x16x32_bf16 v[98:101], v[170:173], v[186:189], v[98:101]
	v_mfma_f32_16x16x32_bf16 v[86:89], v[152:155], v[194:197], v[86:89]
	v_mfma_f32_16x16x32_bf16 v[82:85], v[170:173], v[194:197], v[82:85]
	v_mfma_f32_16x16x32_bf16 v[70:73], v[152:155], v[206:209], v[70:73]
	v_mfma_f32_16x16x32_bf16 v[66:69], v[170:173], v[206:209], v[66:69]
	v_mfma_f32_16x16x32_bf16 v[118:121], v[166:169], v[182:185], v[118:121]
	v_mfma_f32_16x16x32_bf16 v[114:117], v[174:177], v[182:185], v[114:117]
	v_mfma_f32_16x16x32_bf16 v[102:105], v[166:169], v[190:193], v[102:105]
	v_mfma_f32_16x16x32_bf16 v[98:101], v[174:177], v[190:193], v[98:101]
	v_mfma_f32_16x16x32_bf16 v[86:89], v[166:169], v[202:205], v[86:89]
	v_mfma_f32_16x16x32_bf16 v[82:85], v[174:177], v[202:205], v[82:85]
	v_mfma_f32_16x16x32_bf16 v[70:73], v[166:169], v[210:213], v[70:73]
	v_mfma_f32_16x16x32_bf16 v[66:69], v[174:177], v[210:213], v[66:69]
	s_setprio 0
	s_barrier
; #define PG8_STAGE(bufoff, gbase, voff) do { _Pragma("unroll") for (int _i = 0; _i < 2; ++_i) \
;         __builtin_amdgcn_global_load_lds((const unsigned*)((const char*)(gbase) + (voff)[_i]), (PG8_LAS unsigned*)(lds + (bufoff) + ldsw + _i * 8192), 16, 0, 0); } while (0)
; #define PG8_LDA(dst, b, h) do { _Pragma("unroll") for (int m = 0; m < 4; ++m) _Pragma("unroll") for (int k = 0; k < 2; ++k) dst[m][k] = *(const PG8_LAS bf16x8*)(lds + PG8_SA(b, h) + aoff + m * 2048 + k * 1024); } while (0)
; #define PG8_MMA(ai, bj, At, Bt) do { __builtin_amdgcn_s_setprio(1); _Pragma("unroll") for (int m = 0; m < 4; ++m) _Pragma("unroll") for (int n = 0; n < 2; ++n) _Pragma("unroll") for (int k = 0; k < 2; ++k) \
;         acc[ai][bj][m][n] = __builtin_amdgcn_mfma_f32_16x16x32_bf16(Bt[n][k], At[m][k], acc[ai][bj][m][n], 0, 0, 0); __builtin_amdgcn_s_setprio(0); } while (0)
; #define PG8_WAIT_V(n) asm volatile("s_waitcnt vmcnt(" #n ")" ::: "memory")
; #define PG8_WAIT_L(n) asm volatile("s_waitcnt lgkmcnt(" #n ")" ::: "memory")
; #define PG8_BAR __builtin_amdgcn_s_barrier()
; #define PG8_SCHED __builtin_amdgcn_sched_barrier(0)
; template <class Epi, class Sched, bool ALIGN_EPI = false, bool SP2 = false>
; __device__ __forceinline__ void gemm_phase(PG8_LAS unsigned char* lds, const Gemm g, const Sched& S, const Epi& E) {
;     ...
;         for (int t = 0; t < nt; t += 2) {
;             const bool last = (t == nt - 2);
;     ...
;             PG8_LDA(At, 1, 1); PG8_STAGE(PG8_SB(1, 0), b3, voffB); PG8_STAGE(PG8_SB(1, 1), b3 + hstep, voffB); PG8_STAGE(PG8_SA(1, 0), a3, voffA);
;             PG8_WAIT_V(8); PG8_WAIT_L(0); PG8_BAR; PG8_MMA(1, 0, At, B0); PG8_MMA(1, 1, At, B1); PG8_BAR; PG8_SCHED;
	s_add_i32 s61, s61, s0
	v_lshl_add_u64 v[214:215], v[158:159], 0, s[28:29]
	s_mov_b32 m0, s61
	ds_read_b128 v[178:181], v163 offset:49152
	ds_read_b128 v[182:185], v163 offset:50176
	ds_read_b128 v[186:189], v163 offset:51200
	ds_read_b128 v[190:193], v163 offset:52224
	ds_read_b128 v[194:197], v163 offset:53248
	ds_read_b128 v[202:205], v163 offset:54272
	ds_read_b128 v[206:209], v163 offset:55296
	ds_read_b128 v[210:213], v163 offset:56320
	global_load_lds_dwordx4 v[214:215], off
	v_lshl_add_u64 v[214:215], v[158:159], 0, s[30:31]
	s_add_i32 m0, s61, 0x2000
	s_add_i32 s61, s64, s0
	global_load_lds_dwordx4 v[214:215], off
	v_lshl_add_u64 v[214:215], v[158:159], 0, s[34:35]
	s_mov_b32 m0, s61
	v_lshl_add_u64 v[158:159], v[158:159], 0, s[36:37]
	global_load_lds_dwordx4 v[214:215], off
	s_add_i32 m0, s61, 0x2000
	s_nop 0
	global_load_lds_dwordx4 v[158:159], off
	v_lshl_add_u64 v[158:159], v[198:199], 0, s[28:29]
	s_mov_b32 m0, s69
	s_nop 0
	global_load_lds_dwordx4 v[158:159], off
	v_lshl_add_u64 v[158:159], v[198:199], 0, s[30:31]
	s_mov_b32 m0, s70
	s_nop 0
	global_load_lds_dwordx4 v[158:159], off
	s_waitcnt vmcnt(8)
	s_waitcnt lgkmcnt(0)
	s_barrier
	s_setprio 1
	s_waitcnt lgkmcnt(0)
	v_mfma_f32_16x16x32_bf16 v[62:65], v[130:133], v[178:181], v[62:65]
	v_mfma_f32_16x16x32_bf16 v[58:61], v[144:147], v[178:181], v[58:61]
	v_mfma_f32_16x16x32_bf16 v[46:49], v[130:133], v[186:189], v[46:49]
	v_mfma_f32_16x16x32_bf16 v[42:45], v[144:147], v[186:189], v[42:45]
	v_mfma_f32_16x16x32_bf16 v[30:33], v[130:133], v[194:197], v[30:33]
	v_mfma_f32_16x16x32_bf16 v[26:29], v[144:147], v[194:197], v[26:29]
	v_mfma_f32_16x16x32_bf16 v[14:17], v[130:133], v[206:209], v[14:17]
	v_mfma_f32_16x16x32_bf16 v[10:13], v[144:147], v[206:209], v[10:13]
	v_mfma_f32_16x16x32_bf16 v[62:65], v[134:137], v[182:185], v[62:65]
	v_mfma_f32_16x16x32_bf16 v[58:61], v[148:151], v[182:185], v[58:61]
	v_mfma_f32_16x16x32_bf16 v[46:49], v[134:137], v[190:193], v[46:49]
	v_mfma_f32_16x16x32_bf16 v[42:45], v[148:151], v[190:193], v[42:45]
	v_mfma_f32_16x16x32_bf16 v[30:33], v[134:137], v[202:205], v[30:33]
	v_mfma_f32_16x16x32_bf16 v[26:29], v[148:151], v[202:205], v[26:29]
	v_mfma_f32_16x16x32_bf16 v[14:17], v[134:137], v[210:213], v[14:17]
	v_mfma_f32_16x16x32_bf16 v[10:13], v[148:151], v[210:213], v[10:13]
	s_setprio 0
	s_setprio 1
	v_mfma_f32_16x16x32_bf16 v[54:57], v[152:155], v[178:181], v[54:57]
	v_mfma_f32_16x16x32_bf16 v[50:53], v[170:173], v[178:181], v[50:53]
	v_mfma_f32_16x16x32_bf16 v[38:41], v[152:155], v[186:189], v[38:41]
	v_mfma_f32_16x16x32_bf16 v[34:37], v[170:173], v[186:189], v[34:37]
	v_mfma_f32_16x16x32_bf16 v[22:25], v[152:155], v[194:197], v[22:25]
	v_mfma_f32_16x16x32_bf16 v[18:21], v[170:173], v[194:197], v[18:21]
	v_mfma_f32_16x16x32_bf16 v[6:9], v[152:155], v[206:209], v[6:9]
	v_mfma_f32_16x16x32_bf16 v[2:5], v[170:173], v[206:209], v[2:5]
	v_mfma_f32_16x16x32_bf16 v[54:57], v[166:169], v[182:185], v[54:57]
	v_mfma_f32_16x16x32_bf16 v[50:53], v[174:177], v[182:185], v[50:53]
	v_mfma_f32_16x16x32_bf16 v[38:41], v[166:169], v[190:193], v[38:41]
	v_mfma_f32_16x16x32_bf16 v[34:37], v[174:177], v[190:193], v[34:37]
	v_mfma_f32_16x16x32_bf16 v[22:25], v[166:169], v[202:205], v[22:25]
	v_mfma_f32_16x16x32_bf16 v[18:21], v[174:177], v[202:205], v[18:21]
	v_mfma_f32_16x16x32_bf16 v[6:9], v[166:169], v[210:213], v[6:9]
	v_mfma_f32_16x16x32_bf16 v[2:5], v[174:177], v[210:213], v[2:5]
	s_setprio 0
	s_barrier
	s_add_i32 s55, s55, 2
	s_add_u32 s62, s62, 0x8000
	s_addc_u32 s63, s63, 0
	s_add_u32 s51, s51, 0x8000
	s_addc_u32 s53, s53, 0
	s_cmp_gt_u32 s55, 13
	s_cbranch_scc0 .LBB0_881

; #define PG8_STAGE(bufoff, gbase, voff) do { _Pragma("unroll") for (int _i = 0; _i < 2; ++_i) \
;         __builtin_amdgcn_global_load_lds((const unsigned*)((const char*)(gbase) + (voff)[_i]), (PG8_LAS unsigned*)(lds + (bufoff) + ldsw + _i * 8192), 16, 0, 0); } while (0)
; #define PG8_LDA(dst, b, h) do { _Pragma("unroll") for (int m = 0; m < 4; ++m) _Pragma("unroll") for (int k = 0; k < 2; ++k) dst[m][k] = *(const PG8_LAS bf16x8*)(lds + PG8_SA(b, h) + aoff + m * 2048 + k * 1024); } while (0)
; #define PG8_LDB(dst, b, h) do { _Pragma("unroll") for (int n = 0; n < 2; ++n) _Pragma("unroll") for (int k = 0; k < 2; ++k) dst[n][k] = *(const PG8_LAS bf16x8*)(lds + PG8_SB(b, h) + boff + n * 2048 + k * 1024); } while (0)
; #define PG8_MMA(ai, bj, At, Bt) do { __builtin_amdgcn_s_setprio(1); _Pragma("unroll") for (int m = 0; m < 4; ++m) _Pragma("unroll") for (int n = 0; n < 2; ++n) _Pragma("unroll") for (int k = 0; k < 2; ++k) \
;         acc[ai][bj][m][n] = __builtin_amdgcn_mfma_f32_16x16x32_bf16(Bt[n][k], At[m][k], acc[ai][bj][m][n], 0, 0, 0); __builtin_amdgcn_s_setprio(0); } while (0)
; #define PG8_BAR __builtin_amdgcn_s_barrier()
; template <class Epi, class Sched, bool ALIGN_EPI = false, bool SP2 = false>
; __device__ __forceinline__ void gemm_phase(PG8_LAS unsigned char* lds, const Gemm g, const Sched& S, const Epi& E) {
;     ...
;         const bool has_next = S.next(ui + 1, nxt);
;         const char* nA = has_next ? (const char*)g.A + (size_t)nxt.pm * tstep : cA; const char* nB = has_next ? (const char*)g.Bt + (size_t)nxt.pn * tstep : cB;
;         for (int t = 0; t < nt; t += 2) {
;             const bool last = (t == nt - 2);
;             const char* a1 = cA + (size_t)(t + 1) * kstep;
;             const char* a2 = last ? nA : cA + (size_t)(t + 2) * kstep; const char* b2 = last ? nB : cB + (size_t)(t + 2) * kstep;
;             const char* a3 = a2 + kstep; const char* b3 = b2 + kstep;
;             if (last && has_next) S.a_ready(nxt);
;             if constexpr (SP2) {
;             PG8_LDB(B0, 0, 0); PG8_LDB(B1, 0, 1); PG8_SCHED; PG8_LDA(At, 0, 0); PG8_STAGE(PG8_SA(1, 1), a1 + hstep, voffA);
;             PG8_WAIT_V(8); PG8_WAIT_L(0); PG8_BAR; PG8_MMA(0, 0, At, B0); PG8_MMA(0, 1, At, B1); PG8_BAR; PG8_SCHED;
;             PG8_LDA(At, 0, 1); PG8_STAGE(PG8_SB(0, 0), b2, voffB); PG8_STAGE(PG8_SB(0, 1), b2 + hstep, voffB); PG8_STAGE(PG8_SA(0, 0), a2, voffA);
.LBB0_980:
	s_ashr_i32 s39, s38, 31
	s_lshl_b64 s[40:41], s[38:39], 19
	s_add_u32 s40, s1, s40
	s_addc_u32 s41, s33, s41
	s_and_b64 s[42:43], s[2:3], exec
	s_cselect_b32 s39, s41, s13
	s_cselect_b32 s48, s40, s12
	s_ashr_i32 s37, s36, 31
	s_lshl_b64 s[42:43], s[36:37], 19
	s_add_u32 s42, s8, s42
	s_addc_u32 s43, s9, s43
	s_and_b64 s[50:51], s[2:3], exec
	s_cselect_b32 s37, s43, s45
	s_cselect_b32 s49, s42, s44
	s_add_u32 s12, s12, 0x44000
	s_addc_u32 s13, s13, 0
	s_add_u32 s44, s44, 0x8000
	s_addc_u32 s45, s45, 0
	s_mov_b32 s50, -2
	ds_read_b128 v[138:141], v144
	ds_read_b128 v[150:153], v144 offset:1024
	ds_read_b128 v[154:157], v144 offset:2048
	ds_read_b128 v[158:161], v144 offset:3072
	ds_read_b128 v[162:165], v145
	ds_read_b128 v[166:169], v145 offset:1024
	ds_read_b128 v[170:173], v145 offset:2048
	ds_read_b128 v[174:177], v145 offset:3072
	s_add_u32 s51, s12, 0xfffc4000
	s_addc_u32 s67, s13, -1
	s_cmp_eq_u32 s50, 12
	s_cselect_b32 s69, s39, s67
	s_cselect_b32 s68, s48, s51
	s_cselect_b32 s71, s37, s45
	s_cselect_b32 s70, s49, s44
	v_lshl_add_u64 v[198:199], s[12:13], 0, v[130:131]
	s_add_i32 m0, s47, 0xc000
	ds_read_b128 v[178:181], v146
	ds_read_b128 v[182:185], v146 offset:1024
	ds_read_b128 v[186:189], v146 offset:2048
	ds_read_b128 v[190:193], v146 offset:3072
	ds_read_b128 v[194:197], v146 offset:4096
	ds_read_b128 v[202:205], v146 offset:5120
	ds_read_b128 v[206:209], v146 offset:6144
	ds_read_b128 v[210:213], v146 offset:7168
	global_load_lds_dwordx4 v[198:199], off
	v_lshl_add_u64 v[198:199], v[198:199], 0, s[6:7]
	s_add_i32 m0, s47, 0xe000
	s_nop 0
	global_load_lds_dwordx4 v[198:199], off
	s_waitcnt vmcnt(8)
	s_waitcnt lgkmcnt(0)
	s_barrier
	s_setprio 1
	s_waitcnt lgkmcnt(0)
	v_mfma_f32_16x16x32_bf16 v[118:121], v[138:141], v[178:181], 0
	v_mfma_f32_16x16x32_bf16 v[114:117], v[154:157], v[178:181], 0
	v_mfma_f32_16x16x32_bf16 v[102:105], v[138:141], v[186:189], 0
	v_mfma_f32_16x16x32_bf16 v[98:101], v[154:157], v[186:189], 0
	v_mfma_f32_16x16x32_bf16 v[86:89], v[138:141], v[194:197], 0
	v_mfma_f32_16x16x32_bf16 v[82:85], v[154:157], v[194:197], 0
	v_mfma_f32_16x16x32_bf16 v[70:73], v[138:141], v[206:209], 0
	v_mfma_f32_16x16x32_bf16 v[66:69], v[154:157], v[206:209], 0
	v_mfma_f32_16x16x32_bf16 v[118:121], v[150:153], v[182:185], v[118:121]
	v_mfma_f32_16x16x32_bf16 v[114:117], v[158:161], v[182:185], v[114:117]
	v_mfma_f32_16x16x32_bf16 v[102:105], v[150:153], v[190:193], v[102:105]
	v_mfma_f32_16x16x32_bf16 v[98:101], v[158:161], v[190:193], v[98:101]
	v_mfma_f32_16x16x32_bf16 v[86:89], v[150:153], v[202:205], v[86:89]
	v_mfma_f32_16x16x32_bf16 v[82:85], v[158:161], v[202:205], v[82:85]
	v_mfma_f32_16x16x32_bf16 v[70:73], v[150:153], v[210:213], v[70:73]
	v_mfma_f32_16x16x32_bf16 v[66:69], v[158:161], v[210:213], v[66:69]
	s_setprio 0
	s_setprio 1
	v_mfma_f32_16x16x32_bf16 v[126:129], v[162:165], v[178:181], 0
	v_mfma_f32_16x16x32_bf16 v[122:125], v[170:173], v[178:181], 0
	v_mfma_f32_16x16x32_bf16 v[110:113], v[162:165], v[186:189], 0
	v_mfma_f32_16x16x32_bf16 v[106:109], v[170:173], v[186:189], 0
	v_mfma_f32_16x16x32_bf16 v[94:97], v[162:165], v[194:197], 0
	v_mfma_f32_16x16x32_bf16 v[90:93], v[170:173], v[194:197], 0
	v_mfma_f32_16x16x32_bf16 v[78:81], v[162:165], v[206:209], 0
	v_mfma_f32_16x16x32_bf16 v[74:77], v[170:173], v[206:209], 0
	v_mfma_f32_16x16x32_bf16 v[126:129], v[166:169], v[182:185], v[126:129]
	v_mfma_f32_16x16x32_bf16 v[122:125], v[174:177], v[182:185], v[122:125]
	v_mfma_f32_16x16x32_bf16 v[110:113], v[166:169], v[190:193], v[110:113]
	v_mfma_f32_16x16x32_bf16 v[106:109], v[174:177], v[190:193], v[106:109]
	v_mfma_f32_16x16x32_bf16 v[94:97], v[166:169], v[202:205], v[94:97]
	v_mfma_f32_16x16x32_bf16 v[90:93], v[174:177], v[202:205], v[90:93]
	v_mfma_f32_16x16x32_bf16 v[78:81], v[166:169], v[210:213], v[78:81]
	v_mfma_f32_16x16x32_bf16 v[74:77], v[174:177], v[210:213], v[74:77]
	s_setprio 0
	s_barrier
	s_add_i32 s51, s64, s46
	v_lshl_add_u64 v[198:199], s[70:71], 0, v[130:131]
	s_mov_b32 m0, s51
	ds_read_b128 v[178:181], v146 offset:16384
	ds_read_b128 v[182:185], v146 offset:17408
	ds_read_b128 v[186:189], v146 offset:18432
	ds_read_b128 v[190:193], v146 offset:19456
	ds_read_b128 v[194:197], v146 offset:20480
	ds_read_b128 v[202:205], v146 offset:21504
	ds_read_b128 v[206:209], v146 offset:22528
	ds_read_b128 v[210:213], v146 offset:23552
	global_load_lds_dwordx4 v[198:199], off
	v_lshl_add_u64 v[214:215], v[198:199], 0, s[6:7]
	s_add_i32 m0, s51, 0x2000
	s_add_i32 s51, s65, s46
	global_load_lds_dwordx4 v[214:215], off
	v_lshl_add_u64 v[214:215], v[198:199], 0, s[10:11]
	s_mov_b32 m0, s51
	s_nop 0
	global_load_lds_dwordx4 v[214:215], off
	v_lshl_add_u64 v[214:215], v[198:199], 0, s[14:15]
	s_add_i32 m0, s51, 0x2000
	s_nop 0
	global_load_lds_dwordx4 v[214:215], off
	v_lshl_add_u64 v[214:215], s[68:69], 0, v[130:131]
	s_mov_b32 m0, s47
	v_lshl_add_u64 v[216:217], v[214:215], 0, s[6:7]
	global_load_lds_dwordx4 v[214:215], off
	s_mov_b32 m0, s52
	s_nop 0
	global_load_lds_dwordx4 v[216:217], off
	s_waitcnt vmcnt(8)
	s_waitcnt lgkmcnt(0)
	s_barrier
; #define PG8_STAGE(bufoff, gbase, voff) do { _Pragma("unroll") for (int _i = 0; _i < 2; ++_i) \
;         __builtin_amdgcn_global_load_lds((const unsigned*)((const char*)(gbase) + (voff)[_i]), (PG8_LAS unsigned*)(lds + (bufoff) + ldsw + _i * 8192), 16, 0, 0); } while (0)
; #define PG8_LDA(dst, b, h) do { _Pragma("unroll") for (int m = 0; m < 4; ++m) _Pragma("unroll") for (int k = 0; k < 2; ++k) dst[m][k] = *(const PG8_LAS bf16x8*)(lds + PG8_SA(b, h) + aoff + m * 2048 + k * 1024); } while (0)
; #define PG8_LDB(dst, b, h) do { _Pragma("unroll") for (int n = 0; n < 2; ++n) _Pragma("unroll") for (int k = 0; k < 2; ++k) dst[n][k] = *(const PG8_LAS bf16x8*)(lds + PG8_SB(b, h) + boff + n * 2048 + k * 1024); } while (0)
; #define PG8_MMA(ai, bj, At, Bt) do { __builtin_amdgcn_s_setprio(1); _Pragma("unroll") for (int m = 0; m < 4; ++m) _Pragma("unroll") for (int n = 0; n < 2; ++n) _Pragma("unroll") for (int k = 0; k < 2; ++k) \
;         acc[ai][bj][m][n] = __builtin_amdgcn_mfma_f32_16x16x32_bf16(Bt[n][k], At[m][k], acc[ai][bj][m][n], 0, 0, 0); __builtin_amdgcn_s_setprio(0); } while (0)
; #define PG8_WAIT_V(n) asm volatile("s_waitcnt vmcnt(" #n ")" ::: "memory")
; #define PG8_WAIT_L(n) asm volatile("s_waitcnt lgkmcnt(" #n ")" ::: "memory")
; #define PG8_BAR __builtin_amdgcn_s_barrier()
; #define PG8_SCHED __builtin_amdgcn_sched_barrier(0)
; template <class Epi, class Sched, bool ALIGN_EPI = false, bool SP2 = false>
; __device__ __forceinline__ void gemm_phase(PG8_LAS unsigned char* lds, const Gemm g, const Sched& S, const Epi& E) {
;     ...
;             PG8_WAIT_V(8); PG8_WAIT_L(0); PG8_BAR; PG8_MMA(1, 0, At, B0); PG8_MMA(1, 1, At, B1); PG8_BAR; PG8_SCHED;
;             PG8_LDB(B0, 1, 0); PG8_LDB(B1, 1, 1); PG8_SCHED; PG8_LDA(At, 1, 0); PG8_STAGE(PG8_SA(0, 1), a2 + hstep, voffA);
;             PG8_WAIT_V(8); PG8_WAIT_L(0); PG8_BAR; PG8_MMA(0, 0, At, B0); PG8_MMA(0, 1, At, B1); PG8_BAR; PG8_SCHED;
	s_setprio 1
	s_waitcnt lgkmcnt(0)
	v_mfma_f32_16x16x32_bf16 v[54:57], v[138:141], v[178:181], 0
	v_mfma_f32_16x16x32_bf16 v[50:53], v[154:157], v[178:181], 0
	v_mfma_f32_16x16x32_bf16 v[38:41], v[138:141], v[186:189], 0
	v_mfma_f32_16x16x32_bf16 v[34:37], v[154:157], v[186:189], 0
	v_mfma_f32_16x16x32_bf16 v[22:25], v[138:141], v[194:197], 0
	v_mfma_f32_16x16x32_bf16 v[18:21], v[154:157], v[194:197], 0
	v_mfma_f32_16x16x32_bf16 v[6:9], v[138:141], v[206:209], 0
	v_mfma_f32_16x16x32_bf16 v[2:5], v[154:157], v[206:209], 0
	v_mfma_f32_16x16x32_bf16 v[54:57], v[150:153], v[182:185], v[54:57]
	v_mfma_f32_16x16x32_bf16 v[50:53], v[158:161], v[182:185], v[50:53]
	v_mfma_f32_16x16x32_bf16 v[38:41], v[150:153], v[190:193], v[38:41]
	v_mfma_f32_16x16x32_bf16 v[34:37], v[158:161], v[190:193], v[34:37]
	v_mfma_f32_16x16x32_bf16 v[22:25], v[150:153], v[202:205], v[22:25]
	v_mfma_f32_16x16x32_bf16 v[18:21], v[158:161], v[202:205], v[18:21]
	v_mfma_f32_16x16x32_bf16 v[6:9], v[150:153], v[210:213], v[6:9]
	v_mfma_f32_16x16x32_bf16 v[2:5], v[158:161], v[210:213], v[2:5]
	s_setprio 0
	s_setprio 1
	v_mfma_f32_16x16x32_bf16 v[62:65], v[162:165], v[178:181], 0
	v_mfma_f32_16x16x32_bf16 v[58:61], v[170:173], v[178:181], 0
	v_mfma_f32_16x16x32_bf16 v[46:49], v[162:165], v[186:189], 0
	v_mfma_f32_16x16x32_bf16 v[42:45], v[170:173], v[186:189], 0
	v_mfma_f32_16x16x32_bf16 v[30:33], v[162:165], v[194:197], 0
	v_mfma_f32_16x16x32_bf16 v[26:29], v[170:173], v[194:197], 0
	v_mfma_f32_16x16x32_bf16 v[14:17], v[162:165], v[206:209], 0
	v_mfma_f32_16x16x32_bf16 v[10:13], v[170:173], v[206:209], 0
	v_mfma_f32_16x16x32_bf16 v[62:65], v[166:169], v[182:185], v[62:65]
	v_mfma_f32_16x16x32_bf16 v[58:61], v[174:177], v[182:185], v[58:61]
	v_mfma_f32_16x16x32_bf16 v[46:49], v[166:169], v[190:193], v[46:49]
	v_mfma_f32_16x16x32_bf16 v[42:45], v[174:177], v[190:193], v[42:45]
	v_mfma_f32_16x16x32_bf16 v[30:33], v[166:169], v[202:205], v[30:33]
	v_mfma_f32_16x16x32_bf16 v[26:29], v[174:177], v[202:205], v[26:29]
	v_mfma_f32_16x16x32_bf16 v[14:17], v[166:169], v[210:213], v[14:17]
	v_mfma_f32_16x16x32_bf16 v[10:13], v[174:177], v[210:213], v[10:13]
	s_setprio 0
	s_barrier
	s_add_i32 s51, 0, 0x18000
	v_add_u32_e32 v132, s51, v143
	s_add_i32 s67, 0, 0x1c000
	ds_read_b128 v[138:141], v132
	ds_read_b128 v[150:153], v132 offset:1024
	ds_read_b128 v[154:157], v132 offset:2048
	ds_read_b128 v[158:161], v132 offset:3072
	v_add_u32_e32 v132, s67, v143
	ds_read_b128 v[162:165], v132
	ds_read_b128 v[166:169], v132 offset:1024
	ds_read_b128 v[170:173], v132 offset:2048
	ds_read_b128 v[174:177], v132 offset:3072
	s_mov_b32 m0, s53
	v_lshl_add_u64 v[216:217], v[214:215], 0, s[10:11]
	ds_read_b128 v[178:181], v146 offset:32768
	ds_read_b128 v[182:185], v146 offset:33792
	ds_read_b128 v[186:189], v146 offset:34816
	ds_read_b128 v[190:193], v146 offset:35840
	ds_read_b128 v[194:197], v146 offset:36864
	ds_read_b128 v[202:205], v146 offset:37888
	ds_read_b128 v[206:209], v146 offset:38912
	ds_read_b128 v[210:213], v146 offset:39936
	global_load_lds_dwordx4 v[216:217], off
	v_lshl_add_u64 v[216:217], v[214:215], 0, s[14:15]
	s_mov_b32 m0, s54
	s_nop 0
	global_load_lds_dwordx4 v[216:217], off
	s_waitcnt vmcnt(8)
	s_waitcnt lgkmcnt(0)
	s_barrier
	s_setprio 1
	s_waitcnt lgkmcnt(0)
	v_mfma_f32_16x16x32_bf16 v[118:121], v[138:141], v[178:181], v[118:121]
	v_mfma_f32_16x16x32_bf16 v[114:117], v[154:157], v[178:181], v[114:117]
	v_mfma_f32_16x16x32_bf16 v[102:105], v[138:141], v[186:189], v[102:105]
	v_mfma_f32_16x16x32_bf16 v[98:101], v[154:157], v[186:189], v[98:101]
	v_mfma_f32_16x16x32_bf16 v[86:89], v[138:141], v[194:197], v[86:89]
	v_mfma_f32_16x16x32_bf16 v[82:85], v[154:157], v[194:197], v[82:85]
	v_mfma_f32_16x16x32_bf16 v[70:73], v[138:141], v[206:209], v[70:73]
	v_mfma_f32_16x16x32_bf16 v[66:69], v[154:157], v[206:209], v[66:69]
	v_mfma_f32_16x16x32_bf16 v[118:121], v[150:153], v[182:185], v[118:121]
	v_mfma_f32_16x16x32_bf16 v[114:117], v[158:161], v[182:185], v[114:117]
	v_mfma_f32_16x16x32_bf16 v[102:105], v[150:153], v[190:193], v[102:105]
	v_mfma_f32_16x16x32_bf16 v[98:101], v[158:161], v[190:193], v[98:101]
	v_mfma_f32_16x16x32_bf16 v[86:89], v[150:153], v[202:205], v[86:89]
	v_mfma_f32_16x16x32_bf16 v[82:85], v[158:161], v[202:205], v[82:85]
	v_mfma_f32_16x16x32_bf16 v[70:73], v[150:153], v[210:213], v[70:73]
	v_mfma_f32_16x16x32_bf16 v[66:69], v[158:161], v[210:213], v[66:69]
	s_setprio 0
	s_setprio 1
	v_mfma_f32_16x16x32_bf16 v[126:129], v[162:165], v[178:181], v[126:129]
	v_mfma_f32_16x16x32_bf16 v[122:125], v[170:173], v[178:181], v[122:125]
	v_mfma_f32_16x16x32_bf16 v[110:113], v[162:165], v[186:189], v[110:113]
	v_mfma_f32_16x16x32_bf16 v[106:109], v[170:173], v[186:189], v[106:109]
	v_mfma_f32_16x16x32_bf16 v[94:97], v[162:165], v[194:197], v[94:97]
	v_mfma_f32_16x16x32_bf16 v[90:93], v[170:173], v[194:197], v[90:93]
	v_mfma_f32_16x16x32_bf16 v[78:81], v[162:165], v[206:209], v[78:81]
	v_mfma_f32_16x16x32_bf16 v[74:77], v[170:173], v[206:209], v[74:77]
	v_mfma_f32_16x16x32_bf16 v[126:129], v[166:169], v[182:185], v[126:129]
	v_mfma_f32_16x16x32_bf16 v[122:125], v[174:177], v[182:185], v[122:125]
	v_mfma_f32_16x16x32_bf16 v[110:113], v[166:169], v[190:193], v[110:113]
	v_mfma_f32_16x16x32_bf16 v[106:109], v[174:177], v[190:193], v[106:109]
	v_mfma_f32_16x16x32_bf16 v[94:97], v[166:169], v[202:205], v[94:97]
	v_mfma_f32_16x16x32_bf16 v[90:93], v[174:177], v[202:205], v[90:93]
	v_mfma_f32_16x16x32_bf16 v[78:81], v[166:169], v[210:213], v[78:81]
	v_mfma_f32_16x16x32_bf16 v[74:77], v[174:177], v[210:213], v[74:77]
	s_setprio 0
	s_barrier
; #define PG8_STAGE(bufoff, gbase, voff) do { _Pragma("unroll") for (int _i = 0; _i < 2; ++_i) \
;         __builtin_amdgcn_global_load_lds((const unsigned*)((const char*)(gbase) + (voff)[_i]), (PG8_LAS unsigned*)(lds + (bufoff) + ldsw + _i * 8192), 16, 0, 0); } while (0)
; #define PG8_LDA(dst, b, h) do { _Pragma("unroll") for (int m = 0; m < 4; ++m) _Pragma("unroll") for (int k = 0; k < 2; ++k) dst[m][k] = *(const PG8_LAS bf16x8*)(lds + PG8_SA(b, h) + aoff + m * 2048 + k * 1024); } while (0)
; #define PG8_MMA(ai, bj, At, Bt) do { __builtin_amdgcn_s_setprio(1); _Pragma("unroll") for (int m = 0; m < 4; ++m) _Pragma("unroll") for (int n = 0; n < 2; ++n) _Pragma("unroll") for (int k = 0; k < 2; ++k) \
;         acc[ai][bj][m][n] = __builtin_amdgcn_mfma_f32_16x16x32_bf16(Bt[n][k], At[m][k], acc[ai][bj][m][n], 0, 0, 0); __builtin_amdgcn_s_setprio(0); } while (0)
; #define PG8_WAIT_V(n) asm volatile("s_waitcnt vmcnt(" #n ")" ::: "memory")
; #define PG8_WAIT_L(n) asm volatile("s_waitcnt lgkmcnt(" #n ")" ::: "memory")
; #define PG8_BAR __builtin_amdgcn_s_barrier()
; #define PG8_SCHED __builtin_amdgcn_sched_barrier(0)
; template <class Epi, class Sched, bool ALIGN_EPI = false, bool SP2 = false>
; __device__ __forceinline__ void gemm_phase(PG8_LAS unsigned char* lds, const Gemm g, const Sched& S, const Epi& E) {
;     ...
;         for (int t = 0; t < nt; t += 2) {
;             const bool last = (t == nt - 2);
;     ...
;             PG8_LDA(At, 1, 1); PG8_STAGE(PG8_SB(1, 0), b3, voffB); PG8_STAGE(PG8_SB(1, 1), b3 + hstep, voffB); PG8_STAGE(PG8_SA(1, 0), a3, voffA);
;             PG8_WAIT_V(8); PG8_WAIT_L(0); PG8_BAR; PG8_MMA(1, 0, At, B0); PG8_MMA(1, 1, At, B1); PG8_BAR; PG8_SCHED;
	s_add_i32 s51, s51, s46
	v_lshl_add_u64 v[216:217], v[198:199], 0, s[18:19]
	s_mov_b32 m0, s51
	ds_read_b128 v[178:181], v146 offset:49152
	ds_read_b128 v[182:185], v146 offset:50176
	ds_read_b128 v[186:189], v146 offset:51200
	ds_read_b128 v[190:193], v146 offset:52224
	ds_read_b128 v[194:197], v146 offset:53248
	ds_read_b128 v[202:205], v146 offset:54272
	ds_read_b128 v[206:209], v146 offset:55296
	ds_read_b128 v[210:213], v146 offset:56320
	global_load_lds_dwordx4 v[216:217], off
	v_lshl_add_u64 v[216:217], v[198:199], 0, s[20:21]
	s_add_i32 m0, s51, 0x2000
	s_add_i32 s51, s67, s46
	global_load_lds_dwordx4 v[216:217], off
	v_lshl_add_u64 v[216:217], v[198:199], 0, s[22:23]
	s_mov_b32 m0, s51
	v_lshl_add_u64 v[198:199], v[198:199], 0, s[24:25]
	global_load_lds_dwordx4 v[216:217], off
	s_add_i32 m0, s51, 0x2000
	s_nop 0
	global_load_lds_dwordx4 v[198:199], off
	v_lshl_add_u64 v[198:199], v[214:215], 0, s[18:19]
	s_mov_b32 m0, s56
	s_nop 0
	global_load_lds_dwordx4 v[198:199], off
	v_lshl_add_u64 v[198:199], v[214:215], 0, s[20:21]
	s_mov_b32 m0, s57
	s_nop 0
	global_load_lds_dwordx4 v[198:199], off
	s_waitcnt vmcnt(8)
	s_waitcnt lgkmcnt(0)
	s_barrier
	s_setprio 1
	s_waitcnt lgkmcnt(0)
	v_mfma_f32_16x16x32_bf16 v[54:57], v[138:141], v[178:181], v[54:57]
	v_mfma_f32_16x16x32_bf16 v[50:53], v[154:157], v[178:181], v[50:53]
	v_mfma_f32_16x16x32_bf16 v[38:41], v[138:141], v[186:189], v[38:41]
	v_mfma_f32_16x16x32_bf16 v[34:37], v[154:157], v[186:189], v[34:37]
	v_mfma_f32_16x16x32_bf16 v[22:25], v[138:141], v[194:197], v[22:25]
	v_mfma_f32_16x16x32_bf16 v[18:21], v[154:157], v[194:197], v[18:21]
	v_mfma_f32_16x16x32_bf16 v[6:9], v[138:141], v[206:209], v[6:9]
	v_mfma_f32_16x16x32_bf16 v[2:5], v[154:157], v[206:209], v[2:5]
	v_mfma_f32_16x16x32_bf16 v[54:57], v[150:153], v[182:185], v[54:57]
	v_mfma_f32_16x16x32_bf16 v[50:53], v[158:161], v[182:185], v[50:53]
	v_mfma_f32_16x16x32_bf16 v[38:41], v[150:153], v[190:193], v[38:41]
	v_mfma_f32_16x16x32_bf16 v[34:37], v[158:161], v[190:193], v[34:37]
	v_mfma_f32_16x16x32_bf16 v[22:25], v[150:153], v[202:205], v[22:25]
	v_mfma_f32_16x16x32_bf16 v[18:21], v[158:161], v[202:205], v[18:21]
	v_mfma_f32_16x16x32_bf16 v[6:9], v[150:153], v[210:213], v[6:9]
	v_mfma_f32_16x16x32_bf16 v[2:5], v[158:161], v[210:213], v[2:5]
	s_setprio 0
	s_setprio 1
	v_mfma_f32_16x16x32_bf16 v[62:65], v[162:165], v[178:181], v[62:65]
	v_mfma_f32_16x16x32_bf16 v[58:61], v[170:173], v[178:181], v[58:61]
	v_mfma_f32_16x16x32_bf16 v[46:49], v[162:165], v[186:189], v[46:49]
	v_mfma_f32_16x16x32_bf16 v[42:45], v[170:173], v[186:189], v[42:45]
	v_mfma_f32_16x16x32_bf16 v[30:33], v[162:165], v[194:197], v[30:33]
	v_mfma_f32_16x16x32_bf16 v[26:29], v[170:173], v[194:197], v[26:29]
	v_mfma_f32_16x16x32_bf16 v[14:17], v[162:165], v[206:209], v[14:17]
	v_mfma_f32_16x16x32_bf16 v[10:13], v[170:173], v[206:209], v[10:13]
	v_mfma_f32_16x16x32_bf16 v[62:65], v[166:169], v[182:185], v[62:65]
	v_mfma_f32_16x16x32_bf16 v[58:61], v[174:177], v[182:185], v[58:61]
	v_mfma_f32_16x16x32_bf16 v[46:49], v[166:169], v[190:193], v[46:49]
	v_mfma_f32_16x16x32_bf16 v[42:45], v[174:177], v[190:193], v[42:45]
	v_mfma_f32_16x16x32_bf16 v[30:33], v[166:169], v[202:205], v[30:33]
	v_mfma_f32_16x16x32_bf16 v[26:29], v[174:177], v[202:205], v[26:29]
	v_mfma_f32_16x16x32_bf16 v[14:17], v[166:169], v[210:213], v[14:17]
	v_mfma_f32_16x16x32_bf16 v[10:13], v[174:177], v[210:213], v[10:13]
	s_setprio 0
	s_barrier
	s_add_i32 s50, s50, 2
	s_add_u32 s12, s12, 0x8000
	s_addc_u32 s13, s13, 0
	s_add_u32 s44, s44, 0x8000
	s_addc_u32 s45, s45, 0
	s_cmp_gt_u32 s50, 13
	s_cbranch_scc0 .LBB0_981

; #define PG8_STAGE(bufoff, gbase, voff) do { _Pragma("unroll") for (int _i = 0; _i < 2; ++_i) \
;         __builtin_amdgcn_global_load_lds((const unsigned*)((const char*)(gbase) + (voff)[_i]), (PG8_LAS unsigned*)(lds + (bufoff) + ldsw + _i * 8192), 16, 0, 0); } while (0)
; #define PG8_LDA(dst, b, h) do { _Pragma("unroll") for (int m = 0; m < 4; ++m) _Pragma("unroll") for (int k = 0; k < 2; ++k) dst[m][k] = *(const PG8_LAS bf16x8*)(lds + PG8_SA(b, h) + aoff + m * 2048 + k * 1024); } while (0)
; #define PG8_LDB(dst, b, h) do { _Pragma("unroll") for (int n = 0; n < 2; ++n) _Pragma("unroll") for (int k = 0; k < 2; ++k) dst[n][k] = *(const PG8_LAS bf16x8*)(lds + PG8_SB(b, h) + boff + n * 2048 + k * 1024); } while (0)
; #define PG8_MMA(ai, bj, At, Bt) do { __builtin_amdgcn_s_setprio(1); _Pragma("unroll") for (int m = 0; m < 4; ++m) _Pragma("unroll") for (int n = 0; n < 2; ++n) _Pragma("unroll") for (int k = 0; k < 2; ++k) \
;         acc[ai][bj][m][n] = __builtin_amdgcn_mfma_f32_16x16x32_bf16(Bt[n][k], At[m][k], acc[ai][bj][m][n], 0, 0, 0); __builtin_amdgcn_s_setprio(0); } while (0)
; #define PG8_BAR __builtin_amdgcn_s_barrier()
; template <class Epi, class Sched, bool ALIGN_EPI = false, bool SP2 = false>
; __device__ __forceinline__ void gemm_phase(PG8_LAS unsigned char* lds, const Gemm g, const Sched& S, const Epi& E) {
;     ...
;         const bool has_next = S.next(ui + 1, nxt);
;         const char* nA = has_next ? (const char*)g.A + (size_t)nxt.pm * tstep : cA; const char* nB = has_next ? (const char*)g.Bt + (size_t)nxt.pn * tstep : cB;
;         for (int t = 0; t < nt; t += 2) {
;             const bool last = (t == nt - 2);
;             const char* a1 = cA + (size_t)(t + 1) * kstep;
;             const char* a2 = last ? nA : cA + (size_t)(t + 2) * kstep; const char* b2 = last ? nB : cB + (size_t)(t + 2) * kstep;
;             const char* a3 = a2 + kstep; const char* b3 = b2 + kstep;
;             if (last && has_next) S.a_ready(nxt);
;             if constexpr (SP2) {
;             PG8_LDB(B0, 0, 0); PG8_LDB(B1, 0, 1); PG8_SCHED; PG8_LDA(At, 0, 0); PG8_STAGE(PG8_SA(1, 1), a1 + hstep, voffA);
;             PG8_WAIT_V(8); PG8_WAIT_L(0); PG8_BAR; PG8_MMA(0, 0, At, B0); PG8_MMA(0, 1, At, B1); PG8_BAR; PG8_SCHED;
;             PG8_LDA(At, 0, 1); PG8_STAGE(PG8_SB(0, 0), b2, voffB); PG8_STAGE(PG8_SB(0, 1), b2 + hstep, voffB); PG8_STAGE(PG8_SA(0, 0), a2, voffA);
.LBB0_1423:
	s_add_u32 s12, s12, 0xb4000
	s_addc_u32 s13, s13, 0
	s_add_u32 s36, s36, 0x8000
	s_addc_u32 s37, s37, 0
	s_mov_b32 s57, -2
	ds_read_b128 v[136:139], v143
	ds_read_b128 v[146:149], v143 offset:1024
	ds_read_b128 v[150:153], v143 offset:2048
	ds_read_b128 v[154:157], v143 offset:3072
	ds_read_b128 v[158:161], v144
	ds_read_b128 v[162:165], v144 offset:1024
	ds_read_b128 v[166:169], v144 offset:2048
	ds_read_b128 v[170:173], v144 offset:3072
	s_add_u32 s58, s12, 0xfff54000
	s_addc_u32 s59, s13, -1
	s_cmp_eq_u32 s57, 40
	s_cselect_b32 s59, s3, s59
	s_cselect_b32 s58, s2, s58
	s_cselect_b32 s61, s35, s37
	s_cselect_b32 s60, s34, s36
	v_lshl_add_u64 v[198:199], s[12:13], 0, v[128:129]
	s_add_i32 m0, s39, 0xc000
	ds_read_b128 v[174:177], v145
	ds_read_b128 v[178:181], v145 offset:1024
	ds_read_b128 v[182:185], v145 offset:2048
	ds_read_b128 v[186:189], v145 offset:3072
	ds_read_b128 v[190:193], v145 offset:4096
	ds_read_b128 v[194:197], v145 offset:5120
	ds_read_b128 v[202:205], v145 offset:6144
	ds_read_b128 v[206:209], v145 offset:7168
	global_load_lds_dwordx4 v[198:199], off
	v_lshl_add_u64 v[198:199], v[198:199], 0, s[10:11]
	s_add_i32 m0, s39, 0xe000
	s_nop 0
	global_load_lds_dwordx4 v[198:199], off
	s_waitcnt vmcnt(8)
	s_waitcnt lgkmcnt(0)
	s_barrier
	s_setprio 1
	s_waitcnt lgkmcnt(0)
	v_mfma_f32_16x16x32_bf16 v[124:127], v[136:139], v[174:177], 0
	v_mfma_f32_16x16x32_bf16 v[120:123], v[150:153], v[174:177], 0
	v_mfma_f32_16x16x32_bf16 v[108:111], v[136:139], v[182:185], 0
	v_mfma_f32_16x16x32_bf16 v[104:107], v[150:153], v[182:185], 0
	v_mfma_f32_16x16x32_bf16 v[92:95], v[136:139], v[190:193], 0
	v_mfma_f32_16x16x32_bf16 v[88:91], v[150:153], v[190:193], 0
	v_mfma_f32_16x16x32_bf16 v[76:79], v[136:139], v[202:205], 0
	v_mfma_f32_16x16x32_bf16 v[72:75], v[150:153], v[202:205], 0
	v_mfma_f32_16x16x32_bf16 v[124:127], v[146:149], v[178:181], v[124:127]
	v_mfma_f32_16x16x32_bf16 v[120:123], v[154:157], v[178:181], v[120:123]
	v_mfma_f32_16x16x32_bf16 v[108:111], v[146:149], v[186:189], v[108:111]
	v_mfma_f32_16x16x32_bf16 v[104:107], v[154:157], v[186:189], v[104:107]
	v_mfma_f32_16x16x32_bf16 v[92:95], v[146:149], v[194:197], v[92:95]
	v_mfma_f32_16x16x32_bf16 v[88:91], v[154:157], v[194:197], v[88:91]
	v_mfma_f32_16x16x32_bf16 v[76:79], v[146:149], v[206:209], v[76:79]
	v_mfma_f32_16x16x32_bf16 v[72:75], v[154:157], v[206:209], v[72:75]
	s_setprio 0
	s_setprio 1
	v_mfma_f32_16x16x32_bf16 v[116:119], v[158:161], v[174:177], 0
	v_mfma_f32_16x16x32_bf16 v[112:115], v[166:169], v[174:177], 0
	v_mfma_f32_16x16x32_bf16 v[100:103], v[158:161], v[182:185], 0
	v_mfma_f32_16x16x32_bf16 v[96:99], v[166:169], v[182:185], 0
	v_mfma_f32_16x16x32_bf16 v[84:87], v[158:161], v[190:193], 0
	v_mfma_f32_16x16x32_bf16 v[80:83], v[166:169], v[190:193], 0
	v_mfma_f32_16x16x32_bf16 v[68:71], v[158:161], v[202:205], 0
	v_mfma_f32_16x16x32_bf16 v[64:67], v[166:169], v[202:205], 0
	v_mfma_f32_16x16x32_bf16 v[116:119], v[162:165], v[178:181], v[116:119]
	v_mfma_f32_16x16x32_bf16 v[112:115], v[170:173], v[178:181], v[112:115]
	v_mfma_f32_16x16x32_bf16 v[100:103], v[162:165], v[186:189], v[100:103]
	v_mfma_f32_16x16x32_bf16 v[96:99], v[170:173], v[186:189], v[96:99]
	v_mfma_f32_16x16x32_bf16 v[84:87], v[162:165], v[194:197], v[84:87]
	v_mfma_f32_16x16x32_bf16 v[80:83], v[170:173], v[194:197], v[80:83]
	v_mfma_f32_16x16x32_bf16 v[68:71], v[162:165], v[206:209], v[68:71]
	v_mfma_f32_16x16x32_bf16 v[64:67], v[170:173], v[206:209], v[64:67]
	s_setprio 0
	s_barrier
	v_lshl_add_u64 v[198:199], s[60:61], 0, v[128:129]
	s_add_i32 s60, s51, s38
	s_mov_b32 m0, s60
	ds_read_b128 v[174:177], v145 offset:16384
	ds_read_b128 v[178:181], v145 offset:17408
	ds_read_b128 v[182:185], v145 offset:18432
	ds_read_b128 v[186:189], v145 offset:19456
	ds_read_b128 v[190:193], v145 offset:20480
	ds_read_b128 v[194:197], v145 offset:21504
	ds_read_b128 v[202:205], v145 offset:22528
	ds_read_b128 v[206:209], v145 offset:23552
	global_load_lds_dwordx4 v[198:199], off
	v_lshl_add_u64 v[210:211], v[198:199], 0, s[10:11]
	s_add_i32 m0, s60, 0x2000
	s_add_i32 s60, s52, s38
	global_load_lds_dwordx4 v[210:211], off
	v_lshl_add_u64 v[210:211], v[198:199], 0, s[14:15]
	s_mov_b32 m0, s60
	s_nop 0
	global_load_lds_dwordx4 v[210:211], off
	v_lshl_add_u64 v[210:211], v[198:199], 0, s[16:17]
	s_add_i32 m0, s60, 0x2000
	s_nop 0
	global_load_lds_dwordx4 v[210:211], off
	v_lshl_add_u64 v[210:211], s[58:59], 0, v[128:129]
	s_mov_b32 m0, s39
	v_lshl_add_u64 v[212:213], v[210:211], 0, s[10:11]
	global_load_lds_dwordx4 v[210:211], off
	s_mov_b32 m0, s40
	s_nop 0
	global_load_lds_dwordx4 v[212:213], off
	s_waitcnt vmcnt(8)
	s_waitcnt lgkmcnt(0)
	s_barrier
; #define PG8_STAGE(bufoff, gbase, voff) do { _Pragma("unroll") for (int _i = 0; _i < 2; ++_i) \
;         __builtin_amdgcn_global_load_lds((const unsigned*)((const char*)(gbase) + (voff)[_i]), (PG8_LAS unsigned*)(lds + (bufoff) + ldsw + _i * 8192), 16, 0, 0); } while (0)
; #define PG8_LDA(dst, b, h) do { _Pragma("unroll") for (int m = 0; m < 4; ++m) _Pragma("unroll") for (int k = 0; k < 2; ++k) dst[m][k] = *(const PG8_LAS bf16x8*)(lds + PG8_SA(b, h) + aoff + m * 2048 + k * 1024); } while (0)
; #define PG8_LDB(dst, b, h) do { _Pragma("unroll") for (int n = 0; n < 2; ++n) _Pragma("unroll") for (int k = 0; k < 2; ++k) dst[n][k] = *(const PG8_LAS bf16x8*)(lds + PG8_SB(b, h) + boff + n * 2048 + k * 1024); } while (0)
; #define PG8_MMA(ai, bj, At, Bt) do { __builtin_amdgcn_s_setprio(1); _Pragma("unroll") for (int m = 0; m < 4; ++m) _Pragma("unroll") for (int n = 0; n < 2; ++n) _Pragma("unroll") for (int k = 0; k < 2; ++k) \
;         acc[ai][bj][m][n] = __builtin_amdgcn_mfma_f32_16x16x32_bf16(Bt[n][k], At[m][k], acc[ai][bj][m][n], 0, 0, 0); __builtin_amdgcn_s_setprio(0); } while (0)
; #define PG8_WAIT_V(n) asm volatile("s_waitcnt vmcnt(" #n ")" ::: "memory")
; #define PG8_WAIT_L(n) asm volatile("s_waitcnt lgkmcnt(" #n ")" ::: "memory")
; #define PG8_BAR __builtin_amdgcn_s_barrier()
; #define PG8_SCHED __builtin_amdgcn_sched_barrier(0)
; template <class Epi, class Sched, bool ALIGN_EPI = false, bool SP2 = false>
; __device__ __forceinline__ void gemm_phase(PG8_LAS unsigned char* lds, const Gemm g, const Sched& S, const Epi& E) {
;     ...
;             PG8_WAIT_V(8); PG8_WAIT_L(0); PG8_BAR; PG8_MMA(1, 0, At, B0); PG8_MMA(1, 1, At, B1); PG8_BAR; PG8_SCHED;
;             PG8_LDB(B0, 1, 0); PG8_LDB(B1, 1, 1); PG8_SCHED; PG8_LDA(At, 1, 0); PG8_STAGE(PG8_SA(0, 1), a2 + hstep, voffA);
;             PG8_WAIT_V(8); PG8_WAIT_L(0); PG8_BAR; PG8_MMA(0, 0, At, B0); PG8_MMA(0, 1, At, B1); PG8_BAR; PG8_SCHED;
	s_setprio 1
	s_waitcnt lgkmcnt(0)
	v_mfma_f32_16x16x32_bf16 v[60:63], v[136:139], v[174:177], 0
	v_mfma_f32_16x16x32_bf16 v[56:59], v[150:153], v[174:177], 0
	v_mfma_f32_16x16x32_bf16 v[44:47], v[136:139], v[182:185], 0
	v_mfma_f32_16x16x32_bf16 v[40:43], v[150:153], v[182:185], 0
	v_mfma_f32_16x16x32_bf16 v[28:31], v[136:139], v[190:193], 0
	v_mfma_f32_16x16x32_bf16 v[24:27], v[150:153], v[190:193], 0
	v_mfma_f32_16x16x32_bf16 v[12:15], v[136:139], v[202:205], 0
	v_mfma_f32_16x16x32_bf16 v[8:11], v[150:153], v[202:205], 0
	v_mfma_f32_16x16x32_bf16 v[60:63], v[146:149], v[178:181], v[60:63]
	v_mfma_f32_16x16x32_bf16 v[56:59], v[154:157], v[178:181], v[56:59]
	v_mfma_f32_16x16x32_bf16 v[44:47], v[146:149], v[186:189], v[44:47]
	v_mfma_f32_16x16x32_bf16 v[40:43], v[154:157], v[186:189], v[40:43]
	v_mfma_f32_16x16x32_bf16 v[28:31], v[146:149], v[194:197], v[28:31]
	v_mfma_f32_16x16x32_bf16 v[24:27], v[154:157], v[194:197], v[24:27]
	v_mfma_f32_16x16x32_bf16 v[12:15], v[146:149], v[206:209], v[12:15]
	v_mfma_f32_16x16x32_bf16 v[8:11], v[154:157], v[206:209], v[8:11]
	s_setprio 0
	s_setprio 1
	v_mfma_f32_16x16x32_bf16 v[52:55], v[158:161], v[174:177], 0
	v_mfma_f32_16x16x32_bf16 v[48:51], v[166:169], v[174:177], 0
	v_mfma_f32_16x16x32_bf16 v[36:39], v[158:161], v[182:185], 0
	v_mfma_f32_16x16x32_bf16 v[32:35], v[166:169], v[182:185], 0
	v_mfma_f32_16x16x32_bf16 v[20:23], v[158:161], v[190:193], 0
	v_mfma_f32_16x16x32_bf16 v[16:19], v[166:169], v[190:193], 0
	v_mfma_f32_16x16x32_bf16 v[4:7], v[158:161], v[202:205], 0
	v_mfma_f32_16x16x32_bf16 v[0:3], v[166:169], v[202:205], 0
	v_mfma_f32_16x16x32_bf16 v[52:55], v[162:165], v[178:181], v[52:55]
	v_mfma_f32_16x16x32_bf16 v[48:51], v[170:173], v[178:181], v[48:51]
	v_mfma_f32_16x16x32_bf16 v[36:39], v[162:165], v[186:189], v[36:39]
	v_mfma_f32_16x16x32_bf16 v[32:35], v[170:173], v[186:189], v[32:35]
	v_mfma_f32_16x16x32_bf16 v[20:23], v[162:165], v[194:197], v[20:23]
	v_mfma_f32_16x16x32_bf16 v[16:19], v[170:173], v[194:197], v[16:19]
	v_mfma_f32_16x16x32_bf16 v[4:7], v[162:165], v[206:209], v[4:7]
	v_mfma_f32_16x16x32_bf16 v[0:3], v[170:173], v[206:209], v[0:3]
	s_setprio 0
	s_barrier
	s_add_i32 s58, 0, 0x18000
	v_add_u32_e32 v130, s58, v142
	s_add_i32 s59, 0, 0x1c000
	ds_read_b128 v[136:139], v130
	ds_read_b128 v[146:149], v130 offset:1024
	ds_read_b128 v[150:153], v130 offset:2048
	ds_read_b128 v[154:157], v130 offset:3072
	v_add_u32_e32 v130, s59, v142
	ds_read_b128 v[158:161], v130
	ds_read_b128 v[162:165], v130 offset:1024
	ds_read_b128 v[166:169], v130 offset:2048
	ds_read_b128 v[170:173], v130 offset:3072
	s_mov_b32 m0, s41
	v_lshl_add_u64 v[212:213], v[210:211], 0, s[14:15]
	ds_read_b128 v[174:177], v145 offset:32768
	ds_read_b128 v[178:181], v145 offset:33792
	ds_read_b128 v[182:185], v145 offset:34816
	ds_read_b128 v[186:189], v145 offset:35840
	ds_read_b128 v[190:193], v145 offset:36864
	ds_read_b128 v[194:197], v145 offset:37888
	ds_read_b128 v[202:205], v145 offset:38912
	ds_read_b128 v[206:209], v145 offset:39936
	global_load_lds_dwordx4 v[212:213], off
	v_lshl_add_u64 v[212:213], v[210:211], 0, s[16:17]
	s_mov_b32 m0, s42
	s_nop 0
	global_load_lds_dwordx4 v[212:213], off
	s_waitcnt vmcnt(8)
	s_waitcnt lgkmcnt(0)
	s_barrier
	s_setprio 1
	s_waitcnt lgkmcnt(0)
	v_mfma_f32_16x16x32_bf16 v[124:127], v[136:139], v[174:177], v[124:127]
	v_mfma_f32_16x16x32_bf16 v[120:123], v[150:153], v[174:177], v[120:123]
	v_mfma_f32_16x16x32_bf16 v[108:111], v[136:139], v[182:185], v[108:111]
	v_mfma_f32_16x16x32_bf16 v[104:107], v[150:153], v[182:185], v[104:107]
	v_mfma_f32_16x16x32_bf16 v[92:95], v[136:139], v[190:193], v[92:95]
	v_mfma_f32_16x16x32_bf16 v[88:91], v[150:153], v[190:193], v[88:91]
	v_mfma_f32_16x16x32_bf16 v[76:79], v[136:139], v[202:205], v[76:79]
	v_mfma_f32_16x16x32_bf16 v[72:75], v[150:153], v[202:205], v[72:75]
	v_mfma_f32_16x16x32_bf16 v[124:127], v[146:149], v[178:181], v[124:127]
	v_mfma_f32_16x16x32_bf16 v[120:123], v[154:157], v[178:181], v[120:123]
	v_mfma_f32_16x16x32_bf16 v[108:111], v[146:149], v[186:189], v[108:111]
	v_mfma_f32_16x16x32_bf16 v[104:107], v[154:157], v[186:189], v[104:107]
	v_mfma_f32_16x16x32_bf16 v[92:95], v[146:149], v[194:197], v[92:95]
	v_mfma_f32_16x16x32_bf16 v[88:91], v[154:157], v[194:197], v[88:91]
	v_mfma_f32_16x16x32_bf16 v[76:79], v[146:149], v[206:209], v[76:79]
	v_mfma_f32_16x16x32_bf16 v[72:75], v[154:157], v[206:209], v[72:75]
	s_setprio 0
	s_setprio 1
	v_mfma_f32_16x16x32_bf16 v[116:119], v[158:161], v[174:177], v[116:119]
	v_mfma_f32_16x16x32_bf16 v[112:115], v[166:169], v[174:177], v[112:115]
	v_mfma_f32_16x16x32_bf16 v[100:103], v[158:161], v[182:185], v[100:103]
	v_mfma_f32_16x16x32_bf16 v[96:99], v[166:169], v[182:185], v[96:99]
	v_mfma_f32_16x16x32_bf16 v[84:87], v[158:161], v[190:193], v[84:87]
	v_mfma_f32_16x16x32_bf16 v[80:83], v[166:169], v[190:193], v[80:83]
	v_mfma_f32_16x16x32_bf16 v[68:71], v[158:161], v[202:205], v[68:71]
	v_mfma_f32_16x16x32_bf16 v[64:67], v[166:169], v[202:205], v[64:67]
	v_mfma_f32_16x16x32_bf16 v[116:119], v[162:165], v[178:181], v[116:119]
	v_mfma_f32_16x16x32_bf16 v[112:115], v[170:173], v[178:181], v[112:115]
	v_mfma_f32_16x16x32_bf16 v[100:103], v[162:165], v[186:189], v[100:103]
	v_mfma_f32_16x16x32_bf16 v[96:99], v[170:173], v[186:189], v[96:99]
	v_mfma_f32_16x16x32_bf16 v[84:87], v[162:165], v[194:197], v[84:87]
	v_mfma_f32_16x16x32_bf16 v[80:83], v[170:173], v[194:197], v[80:83]
	v_mfma_f32_16x16x32_bf16 v[68:71], v[162:165], v[206:209], v[68:71]
	v_mfma_f32_16x16x32_bf16 v[64:67], v[170:173], v[206:209], v[64:67]
	s_setprio 0
	s_barrier
; #define PG8_STAGE(bufoff, gbase, voff) do { _Pragma("unroll") for (int _i = 0; _i < 2; ++_i) \
;         __builtin_amdgcn_global_load_lds((const unsigned*)((const char*)(gbase) + (voff)[_i]), (PG8_LAS unsigned*)(lds + (bufoff) + ldsw + _i * 8192), 16, 0, 0); } while (0)
; #define PG8_LDA(dst, b, h) do { _Pragma("unroll") for (int m = 0; m < 4; ++m) _Pragma("unroll") for (int k = 0; k < 2; ++k) dst[m][k] = *(const PG8_LAS bf16x8*)(lds + PG8_SA(b, h) + aoff + m * 2048 + k * 1024); } while (0)
; #define PG8_MMA(ai, bj, At, Bt) do { __builtin_amdgcn_s_setprio(1); _Pragma("unroll") for (int m = 0; m < 4; ++m) _Pragma("unroll") for (int n = 0; n < 2; ++n) _Pragma("unroll") for (int k = 0; k < 2; ++k) \
;         acc[ai][bj][m][n] = __builtin_amdgcn_mfma_f32_16x16x32_bf16(Bt[n][k], At[m][k], acc[ai][bj][m][n], 0, 0, 0); __builtin_amdgcn_s_setprio(0); } while (0)
; #define PG8_WAIT_V(n) asm volatile("s_waitcnt vmcnt(" #n ")" ::: "memory")
; #define PG8_WAIT_L(n) asm volatile("s_waitcnt lgkmcnt(" #n ")" ::: "memory")
; #define PG8_BAR __builtin_amdgcn_s_barrier()
; #define PG8_SCHED __builtin_amdgcn_sched_barrier(0)
; template <class Epi, class Sched, bool ALIGN_EPI = false, bool SP2 = false>
; __device__ __forceinline__ void gemm_phase(PG8_LAS unsigned char* lds, const Gemm g, const Sched& S, const Epi& E) {
;     ...
;         for (int t = 0; t < nt; t += 2) {
;             const bool last = (t == nt - 2);
;     ...
;             PG8_LDA(At, 1, 1); PG8_STAGE(PG8_SB(1, 0), b3, voffB); PG8_STAGE(PG8_SB(1, 1), b3 + hstep, voffB); PG8_STAGE(PG8_SA(1, 0), a3, voffA);
;             PG8_WAIT_V(8); PG8_WAIT_L(0); PG8_BAR; PG8_MMA(1, 0, At, B0); PG8_MMA(1, 1, At, B1); PG8_BAR; PG8_SCHED;
	s_add_i32 s58, s58, s38
	v_lshl_add_u64 v[212:213], v[198:199], 0, s[20:21]
	s_mov_b32 m0, s58
	ds_read_b128 v[174:177], v145 offset:49152
	ds_read_b128 v[178:181], v145 offset:50176
	ds_read_b128 v[182:185], v145 offset:51200
	ds_read_b128 v[186:189], v145 offset:52224
	ds_read_b128 v[190:193], v145 offset:53248
	ds_read_b128 v[194:197], v145 offset:54272
	ds_read_b128 v[202:205], v145 offset:55296
	ds_read_b128 v[206:209], v145 offset:56320
	global_load_lds_dwordx4 v[212:213], off
	v_lshl_add_u64 v[212:213], v[198:199], 0, s[22:23]
	s_add_i32 m0, s58, 0x2000
	s_add_i32 s58, s59, s38
	global_load_lds_dwordx4 v[212:213], off
	v_lshl_add_u64 v[212:213], v[198:199], 0, s[24:25]
	s_mov_b32 m0, s58
	v_lshl_add_u64 v[198:199], v[198:199], 0, s[26:27]
	global_load_lds_dwordx4 v[212:213], off
	s_add_i32 m0, s58, 0x2000
	s_nop 0
	global_load_lds_dwordx4 v[198:199], off
	v_lshl_add_u64 v[198:199], v[210:211], 0, s[20:21]
	s_mov_b32 m0, s46
	s_nop 0
	global_load_lds_dwordx4 v[198:199], off
	v_lshl_add_u64 v[198:199], v[210:211], 0, s[22:23]
	s_mov_b32 m0, s47
	s_nop 0
	global_load_lds_dwordx4 v[198:199], off
	s_waitcnt vmcnt(8)
	s_waitcnt lgkmcnt(0)
	s_barrier
	s_setprio 1
	s_waitcnt lgkmcnt(0)
	v_mfma_f32_16x16x32_bf16 v[60:63], v[136:139], v[174:177], v[60:63]
	v_mfma_f32_16x16x32_bf16 v[56:59], v[150:153], v[174:177], v[56:59]
	v_mfma_f32_16x16x32_bf16 v[44:47], v[136:139], v[182:185], v[44:47]
	v_mfma_f32_16x16x32_bf16 v[40:43], v[150:153], v[182:185], v[40:43]
	v_mfma_f32_16x16x32_bf16 v[28:31], v[136:139], v[190:193], v[28:31]
	v_mfma_f32_16x16x32_bf16 v[24:27], v[150:153], v[190:193], v[24:27]
	v_mfma_f32_16x16x32_bf16 v[12:15], v[136:139], v[202:205], v[12:15]
	v_mfma_f32_16x16x32_bf16 v[8:11], v[150:153], v[202:205], v[8:11]
	v_mfma_f32_16x16x32_bf16 v[60:63], v[146:149], v[178:181], v[60:63]
	v_mfma_f32_16x16x32_bf16 v[56:59], v[154:157], v[178:181], v[56:59]
	v_mfma_f32_16x16x32_bf16 v[44:47], v[146:149], v[186:189], v[44:47]
	v_mfma_f32_16x16x32_bf16 v[40:43], v[154:157], v[186:189], v[40:43]
	v_mfma_f32_16x16x32_bf16 v[28:31], v[146:149], v[194:197], v[28:31]
	v_mfma_f32_16x16x32_bf16 v[24:27], v[154:157], v[194:197], v[24:27]
	v_mfma_f32_16x16x32_bf16 v[12:15], v[146:149], v[206:209], v[12:15]
	v_mfma_f32_16x16x32_bf16 v[8:11], v[154:157], v[206:209], v[8:11]
	s_setprio 0
	s_setprio 1
	v_mfma_f32_16x16x32_bf16 v[52:55], v[158:161], v[174:177], v[52:55]
	v_mfma_f32_16x16x32_bf16 v[48:51], v[166:169], v[174:177], v[48:51]
	v_mfma_f32_16x16x32_bf16 v[36:39], v[158:161], v[182:185], v[36:39]
	v_mfma_f32_16x16x32_bf16 v[32:35], v[166:169], v[182:185], v[32:35]
	v_mfma_f32_16x16x32_bf16 v[20:23], v[158:161], v[190:193], v[20:23]
	v_mfma_f32_16x16x32_bf16 v[16:19], v[166:169], v[190:193], v[16:19]
	v_mfma_f32_16x16x32_bf16 v[4:7], v[158:161], v[202:205], v[4:7]
	v_mfma_f32_16x16x32_bf16 v[0:3], v[166:169], v[202:205], v[0:3]
	v_mfma_f32_16x16x32_bf16 v[52:55], v[162:165], v[178:181], v[52:55]
	v_mfma_f32_16x16x32_bf16 v[48:51], v[170:173], v[178:181], v[48:51]
	v_mfma_f32_16x16x32_bf16 v[36:39], v[162:165], v[186:189], v[36:39]
	v_mfma_f32_16x16x32_bf16 v[32:35], v[170:173], v[186:189], v[32:35]
	v_mfma_f32_16x16x32_bf16 v[20:23], v[162:165], v[194:197], v[20:23]
	v_mfma_f32_16x16x32_bf16 v[16:19], v[170:173], v[194:197], v[16:19]
	v_mfma_f32_16x16x32_bf16 v[4:7], v[162:165], v[206:209], v[4:7]
	v_mfma_f32_16x16x32_bf16 v[0:3], v[170:173], v[206:209], v[0:3]
	s_setprio 0
	s_barrier
	s_add_i32 s57, s57, 2
	s_add_u32 s12, s12, 0x8000
	s_addc_u32 s13, s13, 0
	s_add_u32 s36, s36, 0x8000
	s_addc_u32 s37, s37, 0
	s_cmp_gt_u32 s57, 41
	s_cbranch_scc0 .LBB0_1424
